# v4 + GEMM K-loops: barrier hand-off trimmed (redundant post-barrier lgkmcnt(0) removed, s_setprio 1 hoisted before the barrier, mid-block prio flip removed)
# speedup vs baseline: 1.0130x; 1.0042x over previous
.Lrebal_skip_172:
	s_add_i32 m0, s38, 0xc000
	s_nop 0
	global_load_lds_dwordx4 v[160:161], off
	v_lshl_add_u64 v[160:161], s[28:29], 0, v[142:143]
	s_add_i32 m0, s38, 0xe000
	s_nop 0
	global_load_lds_dwordx4 v[160:161], off
	s_waitcnt vmcnt(8)
	s_waitcnt lgkmcnt(0)
	s_setprio 1
	s_barrier
	v_mfma_f32_16x16x32_bf16 v[126:129], v[148:151], v[188:191], v[126:129]
	v_mfma_f32_16x16x32_bf16 v[122:125], v[156:159], v[188:191], v[122:125]
	v_mfma_f32_16x16x32_bf16 v[110:113], v[148:151], v[196:199], v[110:113]
	v_mfma_f32_16x16x32_bf16 v[106:109], v[156:159], v[196:199], v[106:109]
	v_mfma_f32_16x16x32_bf16 v[94:97], v[148:151], v[204:207], v[94:97]
	v_mfma_f32_16x16x32_bf16 v[90:93], v[156:159], v[204:207], v[90:93]
	v_mfma_f32_16x16x32_bf16 v[86:89], v[148:151], v[212:215], v[86:89]
	v_mfma_f32_16x16x32_bf16 v[78:81], v[156:159], v[212:215], v[78:81]
	v_mfma_f32_16x16x32_bf16 v[126:129], v[152:155], v[192:195], v[126:129]
	v_mfma_f32_16x16x32_bf16 v[122:125], v[168:171], v[192:195], v[122:125]
	v_mfma_f32_16x16x32_bf16 v[110:113], v[152:155], v[200:203], v[110:113]
	v_mfma_f32_16x16x32_bf16 v[106:109], v[168:171], v[200:203], v[106:109]
	v_mfma_f32_16x16x32_bf16 v[94:97], v[152:155], v[208:211], v[94:97]
	v_mfma_f32_16x16x32_bf16 v[90:93], v[168:171], v[208:211], v[90:93]
	v_mfma_f32_16x16x32_bf16 v[86:89], v[152:155], v[216:219], v[86:89]
	v_mfma_f32_16x16x32_bf16 v[78:81], v[168:171], v[216:219], v[78:81]
	v_mfma_f32_16x16x32_bf16 v[118:121], v[172:175], v[188:191], v[118:121]
	v_mfma_f32_16x16x32_bf16 v[114:117], v[180:183], v[188:191], v[114:117]
	v_mfma_f32_16x16x32_bf16 v[102:105], v[172:175], v[196:199], v[102:105]
	v_mfma_f32_16x16x32_bf16 v[98:101], v[180:183], v[196:199], v[98:101]
	v_mfma_f32_16x16x32_bf16 v[82:85], v[172:175], v[204:207], v[82:85]
	v_mfma_f32_16x16x32_bf16 v[74:77], v[180:183], v[204:207], v[74:77]
	v_mfma_f32_16x16x32_bf16 v[70:73], v[172:175], v[212:215], v[70:73]
	v_mfma_f32_16x16x32_bf16 v[66:69], v[180:183], v[212:215], v[66:69]
	v_mfma_f32_16x16x32_bf16 v[118:121], v[176:179], v[192:195], v[118:121]
	v_mfma_f32_16x16x32_bf16 v[114:117], v[184:187], v[192:195], v[114:117]
	v_mfma_f32_16x16x32_bf16 v[102:105], v[176:179], v[200:203], v[102:105]
	v_mfma_f32_16x16x32_bf16 v[98:101], v[184:187], v[200:203], v[98:101]
	v_mfma_f32_16x16x32_bf16 v[82:85], v[176:179], v[208:211], v[82:85]
	v_mfma_f32_16x16x32_bf16 v[74:77], v[184:187], v[208:211], v[74:77]
	v_mfma_f32_16x16x32_bf16 v[70:73], v[176:179], v[216:219], v[70:73]
	v_mfma_f32_16x16x32_bf16 v[66:69], v[184:187], v[216:219], v[66:69]
	s_setprio 0
	s_barrier
	s_add_i32 s57, s46, s33
	v_lshl_add_u64 v[160:161], s[30:31], 0, v[134:135]
	s_mov_b32 m0, s57
	ds_read_b128 v[188:191], v167 offset:16384
	ds_read_b128 v[192:195], v167 offset:17408
	ds_read_b128 v[196:199], v167 offset:18432
	ds_read_b128 v[200:203], v167 offset:19456
	ds_read_b128 v[204:207], v167 offset:20480
	ds_read_b128 v[208:211], v167 offset:21504
	ds_read_b128 v[212:215], v167 offset:22528
	ds_read_b128 v[216:219], v167 offset:23552
	global_load_lds_dwordx4 v[160:161], off
	s_add_i32 m0, s57, 0x2000
	s_add_u32 s58, s30, 0x100000
	v_lshl_add_u64 v[220:221], s[30:31], 0, v[130:131]
	s_addc_u32 s59, s31, 0
	s_add_i32 s57, s47, s33
	global_load_lds_dwordx4 v[220:221], off
	v_lshl_add_u64 v[222:223], s[58:59], 0, v[134:135]
	s_mov_b32 m0, s57
	v_lshl_add_u64 v[224:225], s[34:35], 0, v[132:133]
	global_load_lds_dwordx4 v[222:223], off
	v_lshl_add_u64 v[222:223], s[58:59], 0, v[130:131]
	s_add_i32 m0, s57, 0x2000
	s_nop 0
	global_load_lds_dwordx4 v[222:223], off
	v_lshl_add_u64 v[222:223], s[34:35], 0, v[136:137]
	s_waitcnt vmcnt(6)
	s_waitcnt lgkmcnt(0)
	s_setprio 1
	s_barrier
	v_mfma_f32_16x16x32_bf16 v[62:65], v[148:151], v[188:191], v[62:65]
	v_mfma_f32_16x16x32_bf16 v[58:61], v[156:159], v[188:191], v[58:61]
	v_mfma_f32_16x16x32_bf16 v[46:49], v[148:151], v[196:199], v[46:49]
	v_mfma_f32_16x16x32_bf16 v[42:45], v[156:159], v[196:199], v[42:45]
	v_mfma_f32_16x16x32_bf16 v[30:33], v[148:151], v[204:207], v[30:33]
	v_mfma_f32_16x16x32_bf16 v[26:29], v[156:159], v[204:207], v[26:29]
	v_mfma_f32_16x16x32_bf16 v[14:17], v[148:151], v[212:215], v[14:17]
	v_mfma_f32_16x16x32_bf16 v[10:13], v[156:159], v[212:215], v[10:13]
	v_mfma_f32_16x16x32_bf16 v[62:65], v[152:155], v[192:195], v[62:65]
	v_mfma_f32_16x16x32_bf16 v[58:61], v[168:171], v[192:195], v[58:61]
	v_mfma_f32_16x16x32_bf16 v[46:49], v[152:155], v[200:203], v[46:49]
	v_mfma_f32_16x16x32_bf16 v[42:45], v[168:171], v[200:203], v[42:45]
	v_mfma_f32_16x16x32_bf16 v[30:33], v[152:155], v[208:211], v[30:33]
	v_mfma_f32_16x16x32_bf16 v[26:29], v[168:171], v[208:211], v[26:29]
	v_mfma_f32_16x16x32_bf16 v[14:17], v[152:155], v[216:219], v[14:17]
	v_mfma_f32_16x16x32_bf16 v[10:13], v[168:171], v[216:219], v[10:13]
	v_mfma_f32_16x16x32_bf16 v[54:57], v[172:175], v[188:191], v[54:57]
	v_mfma_f32_16x16x32_bf16 v[50:53], v[180:183], v[188:191], v[50:53]
	v_mfma_f32_16x16x32_bf16 v[38:41], v[172:175], v[196:199], v[38:41]
	v_mfma_f32_16x16x32_bf16 v[34:37], v[180:183], v[196:199], v[34:37]
	v_mfma_f32_16x16x32_bf16 v[22:25], v[172:175], v[204:207], v[22:25]
	v_mfma_f32_16x16x32_bf16 v[18:21], v[180:183], v[204:207], v[18:21]
	v_mfma_f32_16x16x32_bf16 v[6:9], v[172:175], v[212:215], v[6:9]
	v_mfma_f32_16x16x32_bf16 v[2:5], v[180:183], v[212:215], v[2:5]
	v_mfma_f32_16x16x32_bf16 v[54:57], v[176:179], v[192:195], v[54:57]
	v_mfma_f32_16x16x32_bf16 v[50:53], v[184:187], v[192:195], v[50:53]
	v_mfma_f32_16x16x32_bf16 v[38:41], v[176:179], v[200:203], v[38:41]
	v_mfma_f32_16x16x32_bf16 v[34:37], v[184:187], v[200:203], v[34:37]
	v_mfma_f32_16x16x32_bf16 v[22:25], v[176:179], v[208:211], v[22:25]
	v_mfma_f32_16x16x32_bf16 v[18:21], v[184:187], v[208:211], v[18:21]
	v_mfma_f32_16x16x32_bf16 v[6:9], v[176:179], v[216:219], v[6:9]
	v_mfma_f32_16x16x32_bf16 v[2:5], v[184:187], v[216:219], v[2:5]
	s_setprio 0
	s_barrier
	s_add_i32 s57, 0, 0x18000
	s_add_i32 s58, 0, 0x1c000
	v_add_u32_e32 v168, s57, v163
	v_add_u32_e32 v184, s58, v163
	ds_read_b128 v[148:151], v168
	ds_read_b128 v[152:155], v168 offset:1024
	ds_read_b128 v[156:159], v168 offset:2048
	ds_read_b128 v[168:171], v168 offset:3072
	ds_read_b128 v[172:175], v184
	ds_read_b128 v[176:179], v184 offset:1024
	ds_read_b128 v[180:183], v184 offset:2048
	ds_read_b128 v[184:187], v184 offset:3072
	s_add_u32 s34, s34, 0x100000
	s_addc_u32 s35, s35, 0
	s_mov_b32 m0, s40
	v_lshl_add_u64 v[226:227], s[34:35], 0, v[136:137]
	ds_read_b128 v[188:191], v167 offset:32768
	ds_read_b128 v[192:195], v167 offset:33792
	ds_read_b128 v[196:199], v167 offset:34816
	ds_read_b128 v[200:203], v167 offset:35840
	ds_read_b128 v[204:207], v167 offset:36864
	ds_read_b128 v[208:211], v167 offset:37888
	ds_read_b128 v[212:215], v167 offset:38912
	ds_read_b128 v[216:219], v167 offset:39936
	s_mov_b32 m0, s38
	s_nop 0
	global_load_lds_dwordx4 v[222:223], off
	s_mov_b32 m0, s39
	s_nop 0
	global_load_lds_dwordx4 v[224:225], off
	s_mov_b32 m0, s40
	s_nop 0
	global_load_lds_dwordx4 v[226:227], off
	v_lshl_add_u64 v[226:227], s[34:35], 0, v[132:133]
	s_mov_b32 m0, s41
	s_nop 0
	global_load_lds_dwordx4 v[226:227], off
	s_waitcnt vmcnt(8)
	s_waitcnt lgkmcnt(0)
	s_setprio 1
	s_barrier
	v_mfma_f32_16x16x32_bf16 v[126:129], v[148:151], v[188:191], v[126:129]
	v_mfma_f32_16x16x32_bf16 v[122:125], v[156:159], v[188:191], v[122:125]
	v_mfma_f32_16x16x32_bf16 v[110:113], v[148:151], v[196:199], v[110:113]
	v_mfma_f32_16x16x32_bf16 v[106:109], v[156:159], v[196:199], v[106:109]
	v_mfma_f32_16x16x32_bf16 v[94:97], v[148:151], v[204:207], v[94:97]
	v_mfma_f32_16x16x32_bf16 v[90:93], v[156:159], v[204:207], v[90:93]
	v_mfma_f32_16x16x32_bf16 v[86:89], v[148:151], v[212:215], v[86:89]
	v_mfma_f32_16x16x32_bf16 v[78:81], v[156:159], v[212:215], v[78:81]
	v_mfma_f32_16x16x32_bf16 v[126:129], v[152:155], v[192:195], v[126:129]
	v_mfma_f32_16x16x32_bf16 v[122:125], v[168:171], v[192:195], v[122:125]
	v_mfma_f32_16x16x32_bf16 v[110:113], v[152:155], v[200:203], v[110:113]
	v_mfma_f32_16x16x32_bf16 v[106:109], v[168:171], v[200:203], v[106:109]
	v_mfma_f32_16x16x32_bf16 v[94:97], v[152:155], v[208:211], v[94:97]
	v_mfma_f32_16x16x32_bf16 v[90:93], v[168:171], v[208:211], v[90:93]
	v_mfma_f32_16x16x32_bf16 v[86:89], v[152:155], v[216:219], v[86:89]
	v_mfma_f32_16x16x32_bf16 v[78:81], v[168:171], v[216:219], v[78:81]
	v_mfma_f32_16x16x32_bf16 v[118:121], v[172:175], v[188:191], v[118:121]
	v_mfma_f32_16x16x32_bf16 v[114:117], v[180:183], v[188:191], v[114:117]
	v_mfma_f32_16x16x32_bf16 v[102:105], v[172:175], v[196:199], v[102:105]
	v_mfma_f32_16x16x32_bf16 v[98:101], v[180:183], v[196:199], v[98:101]
	v_mfma_f32_16x16x32_bf16 v[82:85], v[172:175], v[204:207], v[82:85]
	v_mfma_f32_16x16x32_bf16 v[74:77], v[180:183], v[204:207], v[74:77]
	v_mfma_f32_16x16x32_bf16 v[70:73], v[172:175], v[212:215], v[70:73]
	v_mfma_f32_16x16x32_bf16 v[66:69], v[180:183], v[212:215], v[66:69]
	v_mfma_f32_16x16x32_bf16 v[118:121], v[176:179], v[192:195], v[118:121]
	v_mfma_f32_16x16x32_bf16 v[114:117], v[184:187], v[192:195], v[114:117]
	v_mfma_f32_16x16x32_bf16 v[102:105], v[176:179], v[200:203], v[102:105]
	v_mfma_f32_16x16x32_bf16 v[98:101], v[184:187], v[200:203], v[98:101]
	v_mfma_f32_16x16x32_bf16 v[82:85], v[176:179], v[208:211], v[82:85]
	v_mfma_f32_16x16x32_bf16 v[74:77], v[184:187], v[208:211], v[74:77]
	v_mfma_f32_16x16x32_bf16 v[70:73], v[176:179], v[216:219], v[70:73]
	v_mfma_f32_16x16x32_bf16 v[66:69], v[184:187], v[216:219], v[66:69]
	s_setprio 0
	s_barrier
	s_add_i32 s34, s57, s33
	v_lshl_add_u64 v[160:161], v[160:161], 0, s[8:9]
	s_mov_b32 m0, s34
	ds_read_b128 v[188:191], v167 offset:49152
	ds_read_b128 v[192:195], v167 offset:50176
	ds_read_b128 v[196:199], v167 offset:51200
	ds_read_b128 v[200:203], v167 offset:52224
	ds_read_b128 v[204:207], v167 offset:53248
	ds_read_b128 v[208:211], v167 offset:54272
	ds_read_b128 v[212:215], v167 offset:55296
	ds_read_b128 v[216:219], v167 offset:56320
	global_load_lds_dwordx4 v[160:161], off
	s_add_i32 m0, s34, 0x2000
	s_add_u32 s30, s30, 0x100080
	v_lshl_add_u64 v[160:161], v[220:221], 0, s[8:9]
	s_addc_u32 s31, s31, 0
	s_add_i32 s34, s58, s33
	global_load_lds_dwordx4 v[160:161], off
	v_lshl_add_u64 v[160:161], s[30:31], 0, v[134:135]
	s_mov_b32 m0, s34
	s_nop 0
	global_load_lds_dwordx4 v[160:161], off
	v_lshl_add_u64 v[160:161], s[30:31], 0, v[130:131]
	s_add_i32 m0, s34, 0x2000
	s_nop 0
	global_load_lds_dwordx4 v[160:161], off
	v_lshl_add_u64 v[222:223], v[222:223], 0, s[8:9]
	v_lshl_add_u64 v[224:225], v[224:225], 0, s[8:9]
	s_waitcnt vmcnt(6)
	s_waitcnt lgkmcnt(0)
	s_setprio 1
	s_barrier
	v_mfma_f32_16x16x32_bf16 v[62:65], v[148:151], v[188:191], v[62:65]
	v_mfma_f32_16x16x32_bf16 v[58:61], v[156:159], v[188:191], v[58:61]
	v_mfma_f32_16x16x32_bf16 v[46:49], v[148:151], v[196:199], v[46:49]
	v_mfma_f32_16x16x32_bf16 v[42:45], v[156:159], v[196:199], v[42:45]
	v_mfma_f32_16x16x32_bf16 v[30:33], v[148:151], v[204:207], v[30:33]
	v_mfma_f32_16x16x32_bf16 v[26:29], v[156:159], v[204:207], v[26:29]
	v_mfma_f32_16x16x32_bf16 v[14:17], v[148:151], v[212:215], v[14:17]
	v_mfma_f32_16x16x32_bf16 v[10:13], v[156:159], v[212:215], v[10:13]
	v_mfma_f32_16x16x32_bf16 v[62:65], v[152:155], v[192:195], v[62:65]
	v_mfma_f32_16x16x32_bf16 v[58:61], v[168:171], v[192:195], v[58:61]
	v_mfma_f32_16x16x32_bf16 v[46:49], v[152:155], v[200:203], v[46:49]
	v_mfma_f32_16x16x32_bf16 v[42:45], v[168:171], v[200:203], v[42:45]
	v_mfma_f32_16x16x32_bf16 v[30:33], v[152:155], v[208:211], v[30:33]
	v_mfma_f32_16x16x32_bf16 v[26:29], v[168:171], v[208:211], v[26:29]
	v_mfma_f32_16x16x32_bf16 v[14:17], v[152:155], v[216:219], v[14:17]
	v_mfma_f32_16x16x32_bf16 v[10:13], v[168:171], v[216:219], v[10:13]
	v_mfma_f32_16x16x32_bf16 v[54:57], v[172:175], v[188:191], v[54:57]
	v_mfma_f32_16x16x32_bf16 v[50:53], v[180:183], v[188:191], v[50:53]
	v_mfma_f32_16x16x32_bf16 v[38:41], v[172:175], v[196:199], v[38:41]
	v_mfma_f32_16x16x32_bf16 v[34:37], v[180:183], v[196:199], v[34:37]
	v_mfma_f32_16x16x32_bf16 v[22:25], v[172:175], v[204:207], v[22:25]
	v_mfma_f32_16x16x32_bf16 v[18:21], v[180:183], v[204:207], v[18:21]
	v_mfma_f32_16x16x32_bf16 v[6:9], v[172:175], v[212:215], v[6:9]
	v_mfma_f32_16x16x32_bf16 v[2:5], v[180:183], v[212:215], v[2:5]
	v_mfma_f32_16x16x32_bf16 v[54:57], v[176:179], v[192:195], v[54:57]
	v_mfma_f32_16x16x32_bf16 v[50:53], v[184:187], v[192:195], v[50:53]
	v_mfma_f32_16x16x32_bf16 v[38:41], v[176:179], v[200:203], v[38:41]
	v_mfma_f32_16x16x32_bf16 v[34:37], v[184:187], v[200:203], v[34:37]
	v_mfma_f32_16x16x32_bf16 v[22:25], v[176:179], v[208:211], v[22:25]
	v_mfma_f32_16x16x32_bf16 v[18:21], v[184:187], v[208:211], v[18:21]
	v_mfma_f32_16x16x32_bf16 v[6:9], v[176:179], v[216:219], v[6:9]
	v_mfma_f32_16x16x32_bf16 v[2:5], v[184:187], v[216:219], v[2:5]
	s_setprio 0
	s_barrier
	s_add_i32 s56, s56, 2
	s_mov_b32 s32, 1
	s_add_u32 s28, s28, 0x100
	s_addc_u32 s29, s29, 0
	s_add_u32 s54, s54, 0x100
	s_addc_u32 s55, s55, 0
	s_cmp_gt_u32 s56, 61
	s_cbranch_scc0 .LBB0_172
	s_and_b64 vcc, exec, s[10:11]
	s_cbranch_vccz .LBB0_175
	s_barrier

.Lrebal_skip_696:
	s_add_i32 m0, s21, 0xc000
	s_nop 0
	global_load_lds_dwordx4 v[146:147], off
	v_lshl_add_u64 v[146:147], s[22:23], 0, v[140:141]
	s_add_i32 m0, s21, 0xe000
	s_nop 0
	global_load_lds_dwordx4 v[146:147], off
	s_waitcnt vmcnt(8)
	s_waitcnt lgkmcnt(0)
	s_setprio 1
	s_barrier
	v_mfma_f32_16x16x32_bf16 v[126:129], v[154:157], v[188:191], v[126:129]
	v_mfma_f32_16x16x32_bf16 v[122:125], v[164:167], v[188:191], v[122:125]
	v_mfma_f32_16x16x32_bf16 v[118:121], v[154:157], v[196:199], v[118:121]
	v_mfma_f32_16x16x32_bf16 v[110:113], v[164:167], v[196:199], v[110:113]
	v_mfma_f32_16x16x32_bf16 v[102:105], v[154:157], v[204:207], v[102:105]
	v_mfma_f32_16x16x32_bf16 v[94:97], v[164:167], v[204:207], v[94:97]
	v_mfma_f32_16x16x32_bf16 v[82:85], v[154:157], v[212:215], v[82:85]
	v_mfma_f32_16x16x32_bf16 v[74:77], v[164:167], v[212:215], v[74:77]
	v_mfma_f32_16x16x32_bf16 v[126:129], v[158:161], v[192:195], v[126:129]
	v_mfma_f32_16x16x32_bf16 v[122:125], v[168:171], v[192:195], v[122:125]
	v_mfma_f32_16x16x32_bf16 v[118:121], v[158:161], v[200:203], v[118:121]
	v_mfma_f32_16x16x32_bf16 v[110:113], v[168:171], v[200:203], v[110:113]
	v_mfma_f32_16x16x32_bf16 v[102:105], v[158:161], v[208:211], v[102:105]
	v_mfma_f32_16x16x32_bf16 v[94:97], v[168:171], v[208:211], v[94:97]
	v_mfma_f32_16x16x32_bf16 v[82:85], v[158:161], v[216:219], v[82:85]
	v_mfma_f32_16x16x32_bf16 v[74:77], v[168:171], v[216:219], v[74:77]
	v_mfma_f32_16x16x32_bf16 v[114:117], v[172:175], v[188:191], v[114:117]
	v_mfma_f32_16x16x32_bf16 v[106:109], v[180:183], v[188:191], v[106:109]
	v_mfma_f32_16x16x32_bf16 v[98:101], v[172:175], v[196:199], v[98:101]
	v_mfma_f32_16x16x32_bf16 v[90:93], v[180:183], v[196:199], v[90:93]
	v_mfma_f32_16x16x32_bf16 v[86:89], v[172:175], v[204:207], v[86:89]
	v_mfma_f32_16x16x32_bf16 v[78:81], v[180:183], v[204:207], v[78:81]
	v_mfma_f32_16x16x32_bf16 v[70:73], v[172:175], v[212:215], v[70:73]
	v_mfma_f32_16x16x32_bf16 v[66:69], v[180:183], v[212:215], v[66:69]
	v_mfma_f32_16x16x32_bf16 v[114:117], v[176:179], v[192:195], v[114:117]
	v_mfma_f32_16x16x32_bf16 v[106:109], v[184:187], v[192:195], v[106:109]
	v_mfma_f32_16x16x32_bf16 v[98:101], v[176:179], v[200:203], v[98:101]
	v_mfma_f32_16x16x32_bf16 v[90:93], v[184:187], v[200:203], v[90:93]
	v_mfma_f32_16x16x32_bf16 v[86:89], v[176:179], v[208:211], v[86:89]
	v_mfma_f32_16x16x32_bf16 v[78:81], v[184:187], v[208:211], v[78:81]
	v_mfma_f32_16x16x32_bf16 v[70:73], v[176:179], v[216:219], v[70:73]
	v_mfma_f32_16x16x32_bf16 v[66:69], v[184:187], v[216:219], v[66:69]
	s_setprio 0
	s_barrier
	s_add_i32 s48, s38, s29
	v_lshl_add_u64 v[146:147], s[24:25], 0, v[132:133]
	s_mov_b32 m0, s48
	ds_read_b128 v[188:191], v152 offset:16384
	ds_read_b128 v[192:195], v152 offset:17408
	ds_read_b128 v[196:199], v152 offset:18432
	ds_read_b128 v[200:203], v152 offset:19456
	ds_read_b128 v[204:207], v152 offset:20480
	ds_read_b128 v[208:211], v152 offset:21504
	ds_read_b128 v[212:215], v152 offset:22528
	ds_read_b128 v[216:219], v152 offset:23552
	global_load_lds_dwordx4 v[146:147], off
	s_add_i32 m0, s48, 0x2000
	s_add_u32 s48, s24, 0x100000
	v_lshl_add_u64 v[220:221], s[24:25], 0, v[136:137]
	s_addc_u32 s49, s25, 0
	s_add_i32 s50, s39, s29
	global_load_lds_dwordx4 v[220:221], off
	v_lshl_add_u64 v[222:223], s[48:49], 0, v[132:133]
	s_mov_b32 m0, s50
	v_lshl_add_u64 v[224:225], s[26:27], 0, v[134:135]
	global_load_lds_dwordx4 v[222:223], off
	v_lshl_add_u64 v[222:223], s[48:49], 0, v[136:137]
	s_add_i32 m0, s50, 0x2000
	s_nop 0
	global_load_lds_dwordx4 v[222:223], off
	v_lshl_add_u64 v[222:223], s[26:27], 0, v[130:131]
	s_waitcnt vmcnt(6)
	s_waitcnt lgkmcnt(0)
	s_setprio 1
	s_barrier
	v_mfma_f32_16x16x32_bf16 v[62:65], v[154:157], v[188:191], v[62:65]
	v_mfma_f32_16x16x32_bf16 v[58:61], v[164:167], v[188:191], v[58:61]
	v_mfma_f32_16x16x32_bf16 v[54:57], v[154:157], v[196:199], v[54:57]
	v_mfma_f32_16x16x32_bf16 v[46:49], v[164:167], v[196:199], v[46:49]
	v_mfma_f32_16x16x32_bf16 v[38:41], v[154:157], v[204:207], v[38:41]
	v_mfma_f32_16x16x32_bf16 v[30:33], v[164:167], v[204:207], v[30:33]
	v_mfma_f32_16x16x32_bf16 v[22:25], v[154:157], v[212:215], v[22:25]
	v_mfma_f32_16x16x32_bf16 v[14:17], v[164:167], v[212:215], v[14:17]
	v_mfma_f32_16x16x32_bf16 v[62:65], v[158:161], v[192:195], v[62:65]
	v_mfma_f32_16x16x32_bf16 v[58:61], v[168:171], v[192:195], v[58:61]
	v_mfma_f32_16x16x32_bf16 v[54:57], v[158:161], v[200:203], v[54:57]
	v_mfma_f32_16x16x32_bf16 v[46:49], v[168:171], v[200:203], v[46:49]
	v_mfma_f32_16x16x32_bf16 v[38:41], v[158:161], v[208:211], v[38:41]
	v_mfma_f32_16x16x32_bf16 v[30:33], v[168:171], v[208:211], v[30:33]
	v_mfma_f32_16x16x32_bf16 v[22:25], v[158:161], v[216:219], v[22:25]
	v_mfma_f32_16x16x32_bf16 v[14:17], v[168:171], v[216:219], v[14:17]
	v_mfma_f32_16x16x32_bf16 v[50:53], v[172:175], v[188:191], v[50:53]
	v_mfma_f32_16x16x32_bf16 v[42:45], v[180:183], v[188:191], v[42:45]
	v_mfma_f32_16x16x32_bf16 v[34:37], v[172:175], v[196:199], v[34:37]
	v_mfma_f32_16x16x32_bf16 v[26:29], v[180:183], v[196:199], v[26:29]
	v_mfma_f32_16x16x32_bf16 v[18:21], v[172:175], v[204:207], v[18:21]
	v_mfma_f32_16x16x32_bf16 v[10:13], v[180:183], v[204:207], v[10:13]
	v_mfma_f32_16x16x32_bf16 v[6:9], v[172:175], v[212:215], v[6:9]
	v_mfma_f32_16x16x32_bf16 v[2:5], v[180:183], v[212:215], v[2:5]
	v_mfma_f32_16x16x32_bf16 v[50:53], v[176:179], v[192:195], v[50:53]
	v_mfma_f32_16x16x32_bf16 v[42:45], v[184:187], v[192:195], v[42:45]
	v_mfma_f32_16x16x32_bf16 v[34:37], v[176:179], v[200:203], v[34:37]
	v_mfma_f32_16x16x32_bf16 v[26:29], v[184:187], v[200:203], v[26:29]
	v_mfma_f32_16x16x32_bf16 v[18:21], v[176:179], v[208:211], v[18:21]
	v_mfma_f32_16x16x32_bf16 v[10:13], v[184:187], v[208:211], v[10:13]
	v_mfma_f32_16x16x32_bf16 v[6:9], v[176:179], v[216:219], v[6:9]
	v_mfma_f32_16x16x32_bf16 v[2:5], v[184:187], v[216:219], v[2:5]
	s_setprio 0
	s_barrier
	s_add_i32 s48, 0, 0x18000
	v_add_u32_e32 v153, s48, v148
	s_add_i32 s49, 0, 0x1c000
	ds_read_b128 v[154:157], v153
	ds_read_b128 v[158:161], v153 offset:1024
	ds_read_b128 v[164:167], v153 offset:2048
	ds_read_b128 v[168:171], v153 offset:3072
	v_add_u32_e32 v153, s49, v148
	ds_read_b128 v[172:175], v153
	ds_read_b128 v[176:179], v153 offset:1024
	ds_read_b128 v[180:183], v153 offset:2048
	ds_read_b128 v[184:187], v153 offset:3072
	s_add_u32 s26, s26, 0x100000
	s_addc_u32 s27, s27, 0
	s_mov_b32 m0, s31
	v_lshl_add_u64 v[226:227], s[26:27], 0, v[130:131]
	ds_read_b128 v[188:191], v152 offset:32768
	ds_read_b128 v[192:195], v152 offset:33792
	ds_read_b128 v[196:199], v152 offset:34816
	ds_read_b128 v[200:203], v152 offset:35840
	ds_read_b128 v[204:207], v152 offset:36864
	ds_read_b128 v[208:211], v152 offset:37888
	ds_read_b128 v[212:215], v152 offset:38912
	ds_read_b128 v[216:219], v152 offset:39936
	s_mov_b32 m0, s21
	s_nop 0
	global_load_lds_dwordx4 v[222:223], off
	s_mov_b32 m0, s30
	s_nop 0
	global_load_lds_dwordx4 v[224:225], off
	s_mov_b32 m0, s31
	s_nop 0
	global_load_lds_dwordx4 v[226:227], off
	v_lshl_add_u64 v[226:227], s[26:27], 0, v[134:135]
	s_mov_b32 m0, s33
	s_nop 0
	global_load_lds_dwordx4 v[226:227], off
	s_waitcnt vmcnt(8)
	s_waitcnt lgkmcnt(0)
	s_setprio 1
	s_barrier
	v_mfma_f32_16x16x32_bf16 v[126:129], v[154:157], v[188:191], v[126:129]
	v_mfma_f32_16x16x32_bf16 v[122:125], v[164:167], v[188:191], v[122:125]
	v_mfma_f32_16x16x32_bf16 v[118:121], v[154:157], v[196:199], v[118:121]
	v_mfma_f32_16x16x32_bf16 v[110:113], v[164:167], v[196:199], v[110:113]
	v_mfma_f32_16x16x32_bf16 v[102:105], v[154:157], v[204:207], v[102:105]
	v_mfma_f32_16x16x32_bf16 v[94:97], v[164:167], v[204:207], v[94:97]
	v_mfma_f32_16x16x32_bf16 v[82:85], v[154:157], v[212:215], v[82:85]
	v_mfma_f32_16x16x32_bf16 v[74:77], v[164:167], v[212:215], v[74:77]
	v_mfma_f32_16x16x32_bf16 v[126:129], v[158:161], v[192:195], v[126:129]
	v_mfma_f32_16x16x32_bf16 v[122:125], v[168:171], v[192:195], v[122:125]
	v_mfma_f32_16x16x32_bf16 v[118:121], v[158:161], v[200:203], v[118:121]
	v_mfma_f32_16x16x32_bf16 v[110:113], v[168:171], v[200:203], v[110:113]
	v_mfma_f32_16x16x32_bf16 v[102:105], v[158:161], v[208:211], v[102:105]
	v_mfma_f32_16x16x32_bf16 v[94:97], v[168:171], v[208:211], v[94:97]
	v_mfma_f32_16x16x32_bf16 v[82:85], v[158:161], v[216:219], v[82:85]
	v_mfma_f32_16x16x32_bf16 v[74:77], v[168:171], v[216:219], v[74:77]
	v_mfma_f32_16x16x32_bf16 v[114:117], v[172:175], v[188:191], v[114:117]
	v_mfma_f32_16x16x32_bf16 v[106:109], v[180:183], v[188:191], v[106:109]
	v_mfma_f32_16x16x32_bf16 v[98:101], v[172:175], v[196:199], v[98:101]
	v_mfma_f32_16x16x32_bf16 v[90:93], v[180:183], v[196:199], v[90:93]
	v_mfma_f32_16x16x32_bf16 v[86:89], v[172:175], v[204:207], v[86:89]
	v_mfma_f32_16x16x32_bf16 v[78:81], v[180:183], v[204:207], v[78:81]
	v_mfma_f32_16x16x32_bf16 v[70:73], v[172:175], v[212:215], v[70:73]
	v_mfma_f32_16x16x32_bf16 v[66:69], v[180:183], v[212:215], v[66:69]
	v_mfma_f32_16x16x32_bf16 v[114:117], v[176:179], v[192:195], v[114:117]
	v_mfma_f32_16x16x32_bf16 v[106:109], v[184:187], v[192:195], v[106:109]
	v_mfma_f32_16x16x32_bf16 v[98:101], v[176:179], v[200:203], v[98:101]
	v_mfma_f32_16x16x32_bf16 v[90:93], v[184:187], v[200:203], v[90:93]
	v_mfma_f32_16x16x32_bf16 v[86:89], v[176:179], v[208:211], v[86:89]
	v_mfma_f32_16x16x32_bf16 v[78:81], v[184:187], v[208:211], v[78:81]
	v_mfma_f32_16x16x32_bf16 v[70:73], v[176:179], v[216:219], v[70:73]
	v_mfma_f32_16x16x32_bf16 v[66:69], v[184:187], v[216:219], v[66:69]
	s_setprio 0
	s_barrier
	s_add_i32 s26, s48, s29
	v_lshl_add_u64 v[146:147], v[146:147], 0, s[6:7]
	s_mov_b32 m0, s26
	ds_read_b128 v[188:191], v152 offset:49152
	ds_read_b128 v[192:195], v152 offset:50176
	ds_read_b128 v[196:199], v152 offset:51200
	ds_read_b128 v[200:203], v152 offset:52224
	ds_read_b128 v[204:207], v152 offset:53248
	ds_read_b128 v[208:211], v152 offset:54272
	ds_read_b128 v[212:215], v152 offset:55296
	ds_read_b128 v[216:219], v152 offset:56320
	global_load_lds_dwordx4 v[146:147], off
	s_add_i32 m0, s26, 0x2000
	s_add_u32 s24, s24, 0x100080
	v_lshl_add_u64 v[146:147], v[220:221], 0, s[6:7]
	s_addc_u32 s25, s25, 0
	s_add_i32 s26, s49, s29
	global_load_lds_dwordx4 v[146:147], off
	v_lshl_add_u64 v[146:147], s[24:25], 0, v[132:133]
	s_mov_b32 m0, s26
	s_nop 0
	global_load_lds_dwordx4 v[146:147], off
	v_lshl_add_u64 v[146:147], s[24:25], 0, v[136:137]
	s_add_i32 m0, s26, 0x2000
	s_nop 0
	global_load_lds_dwordx4 v[146:147], off
	v_lshl_add_u64 v[222:223], v[222:223], 0, s[6:7]
	v_lshl_add_u64 v[224:225], v[224:225], 0, s[6:7]
	s_waitcnt vmcnt(6)
	s_waitcnt lgkmcnt(0)
	s_setprio 1
	s_barrier
	v_mfma_f32_16x16x32_bf16 v[62:65], v[154:157], v[188:191], v[62:65]
	v_mfma_f32_16x16x32_bf16 v[58:61], v[164:167], v[188:191], v[58:61]
	v_mfma_f32_16x16x32_bf16 v[54:57], v[154:157], v[196:199], v[54:57]
	v_mfma_f32_16x16x32_bf16 v[46:49], v[164:167], v[196:199], v[46:49]
	v_mfma_f32_16x16x32_bf16 v[38:41], v[154:157], v[204:207], v[38:41]
	v_mfma_f32_16x16x32_bf16 v[30:33], v[164:167], v[204:207], v[30:33]
	v_mfma_f32_16x16x32_bf16 v[22:25], v[154:157], v[212:215], v[22:25]
	v_mfma_f32_16x16x32_bf16 v[14:17], v[164:167], v[212:215], v[14:17]
	v_mfma_f32_16x16x32_bf16 v[62:65], v[158:161], v[192:195], v[62:65]
	v_mfma_f32_16x16x32_bf16 v[58:61], v[168:171], v[192:195], v[58:61]
	v_mfma_f32_16x16x32_bf16 v[54:57], v[158:161], v[200:203], v[54:57]
	v_mfma_f32_16x16x32_bf16 v[46:49], v[168:171], v[200:203], v[46:49]
	v_mfma_f32_16x16x32_bf16 v[38:41], v[158:161], v[208:211], v[38:41]
	v_mfma_f32_16x16x32_bf16 v[30:33], v[168:171], v[208:211], v[30:33]
	v_mfma_f32_16x16x32_bf16 v[22:25], v[158:161], v[216:219], v[22:25]
	v_mfma_f32_16x16x32_bf16 v[14:17], v[168:171], v[216:219], v[14:17]
	v_mfma_f32_16x16x32_bf16 v[50:53], v[172:175], v[188:191], v[50:53]
	v_mfma_f32_16x16x32_bf16 v[42:45], v[180:183], v[188:191], v[42:45]
	v_mfma_f32_16x16x32_bf16 v[34:37], v[172:175], v[196:199], v[34:37]
	v_mfma_f32_16x16x32_bf16 v[26:29], v[180:183], v[196:199], v[26:29]
	v_mfma_f32_16x16x32_bf16 v[18:21], v[172:175], v[204:207], v[18:21]
	v_mfma_f32_16x16x32_bf16 v[10:13], v[180:183], v[204:207], v[10:13]
	v_mfma_f32_16x16x32_bf16 v[6:9], v[172:175], v[212:215], v[6:9]
	v_mfma_f32_16x16x32_bf16 v[2:5], v[180:183], v[212:215], v[2:5]
	v_mfma_f32_16x16x32_bf16 v[50:53], v[176:179], v[192:195], v[50:53]
	v_mfma_f32_16x16x32_bf16 v[42:45], v[184:187], v[192:195], v[42:45]
	v_mfma_f32_16x16x32_bf16 v[34:37], v[176:179], v[200:203], v[34:37]
	v_mfma_f32_16x16x32_bf16 v[26:29], v[184:187], v[200:203], v[26:29]
	v_mfma_f32_16x16x32_bf16 v[18:21], v[176:179], v[208:211], v[18:21]
	v_mfma_f32_16x16x32_bf16 v[10:13], v[184:187], v[208:211], v[10:13]
	v_mfma_f32_16x16x32_bf16 v[6:9], v[176:179], v[216:219], v[6:9]
	v_mfma_f32_16x16x32_bf16 v[2:5], v[184:187], v[216:219], v[2:5]
	s_setprio 0
	s_barrier
	s_add_i32 s47, s47, 2
	s_mov_b32 s32, 1
	s_add_u32 s22, s22, 0x100
	s_addc_u32 s23, s23, 0
	s_add_u32 s45, s45, 0x100
	s_addc_u32 s46, s46, 0
	s_cmp_gt_u32 s47, 61
	s_cbranch_scc0 .LBB0_696
	s_and_b64 vcc, exec, s[8:9]
	s_cbranch_vccz .LBB0_699
	s_barrier

.Lrebal_skip_820:
	s_add_i32 m0, s23, 0xc000
	s_nop 0
	global_load_lds_dwordx4 v[220:221], off
	v_lshl_add_u64 v[220:221], s[24:25], 0, v[140:141]
	s_add_i32 m0, s23, 0xe000
	s_nop 0
	global_load_lds_dwordx4 v[220:221], off
	s_waitcnt vmcnt(8)
	s_waitcnt lgkmcnt(0)
	s_setprio 1
	s_barrier
	v_mfma_f32_16x16x32_bf16 v[126:129], v[146:149], v[188:191], v[126:129]
	v_mfma_f32_16x16x32_bf16 v[122:125], v[164:167], v[188:191], v[122:125]
	v_mfma_f32_16x16x32_bf16 v[110:113], v[146:149], v[196:199], v[110:113]
	v_mfma_f32_16x16x32_bf16 v[106:109], v[164:167], v[196:199], v[106:109]
	v_mfma_f32_16x16x32_bf16 v[94:97], v[146:149], v[204:207], v[94:97]
	v_mfma_f32_16x16x32_bf16 v[90:93], v[164:167], v[204:207], v[90:93]
	v_mfma_f32_16x16x32_bf16 v[78:81], v[146:149], v[212:215], v[78:81]
	v_mfma_f32_16x16x32_bf16 v[74:77], v[164:167], v[212:215], v[74:77]
	v_mfma_f32_16x16x32_bf16 v[126:129], v[158:161], v[192:195], v[126:129]
	v_mfma_f32_16x16x32_bf16 v[122:125], v[168:171], v[192:195], v[122:125]
	v_mfma_f32_16x16x32_bf16 v[110:113], v[158:161], v[200:203], v[110:113]
	v_mfma_f32_16x16x32_bf16 v[106:109], v[168:171], v[200:203], v[106:109]
	v_mfma_f32_16x16x32_bf16 v[94:97], v[158:161], v[208:211], v[94:97]
	v_mfma_f32_16x16x32_bf16 v[90:93], v[168:171], v[208:211], v[90:93]
	v_mfma_f32_16x16x32_bf16 v[78:81], v[158:161], v[216:219], v[78:81]
	v_mfma_f32_16x16x32_bf16 v[74:77], v[168:171], v[216:219], v[74:77]
	v_mfma_f32_16x16x32_bf16 v[118:121], v[172:175], v[188:191], v[118:121]
	v_mfma_f32_16x16x32_bf16 v[114:117], v[180:183], v[188:191], v[114:117]
	v_mfma_f32_16x16x32_bf16 v[102:105], v[172:175], v[196:199], v[102:105]
	v_mfma_f32_16x16x32_bf16 v[98:101], v[180:183], v[196:199], v[98:101]
	v_mfma_f32_16x16x32_bf16 v[86:89], v[172:175], v[204:207], v[86:89]
	v_mfma_f32_16x16x32_bf16 v[82:85], v[180:183], v[204:207], v[82:85]
	v_mfma_f32_16x16x32_bf16 v[70:73], v[172:175], v[212:215], v[70:73]
	v_mfma_f32_16x16x32_bf16 v[66:69], v[180:183], v[212:215], v[66:69]
	v_mfma_f32_16x16x32_bf16 v[118:121], v[176:179], v[192:195], v[118:121]
	v_mfma_f32_16x16x32_bf16 v[114:117], v[184:187], v[192:195], v[114:117]
	v_mfma_f32_16x16x32_bf16 v[102:105], v[176:179], v[200:203], v[102:105]
	v_mfma_f32_16x16x32_bf16 v[98:101], v[184:187], v[200:203], v[98:101]
	v_mfma_f32_16x16x32_bf16 v[86:89], v[176:179], v[208:211], v[86:89]
	v_mfma_f32_16x16x32_bf16 v[82:85], v[184:187], v[208:211], v[82:85]
	v_mfma_f32_16x16x32_bf16 v[70:73], v[176:179], v[216:219], v[70:73]
	v_mfma_f32_16x16x32_bf16 v[66:69], v[184:187], v[216:219], v[66:69]
	s_setprio 0
	s_barrier
	s_add_i32 s48, s41, s30
	v_lshl_add_u64 v[220:221], s[26:27], 0, v[132:133]
	s_mov_b32 m0, s48
	ds_read_b128 v[188:191], v156 offset:16384
	ds_read_b128 v[192:195], v156 offset:17408
	ds_read_b128 v[196:199], v156 offset:18432
	ds_read_b128 v[200:203], v156 offset:19456
	ds_read_b128 v[204:207], v156 offset:20480
	ds_read_b128 v[208:211], v156 offset:21504
	ds_read_b128 v[212:215], v156 offset:22528
	ds_read_b128 v[216:219], v156 offset:23552
	global_load_lds_dwordx4 v[220:221], off
	s_add_i32 m0, s48, 0x2000
	s_add_u32 s48, s26, 0x100000
	v_lshl_add_u64 v[222:223], s[26:27], 0, v[136:137]
	s_addc_u32 s49, s27, 0
	s_add_i32 s50, s42, s30
	global_load_lds_dwordx4 v[222:223], off
	v_lshl_add_u64 v[224:225], s[48:49], 0, v[132:133]
	s_mov_b32 m0, s50
	v_lshl_add_u64 v[226:227], s[28:29], 0, v[134:135]
	global_load_lds_dwordx4 v[224:225], off
	v_lshl_add_u64 v[224:225], s[48:49], 0, v[136:137]
	s_add_i32 m0, s50, 0x2000
	s_nop 0
	global_load_lds_dwordx4 v[224:225], off
	v_lshl_add_u64 v[224:225], s[28:29], 0, v[130:131]
	s_waitcnt vmcnt(6)
	s_waitcnt lgkmcnt(0)
	s_setprio 1
	s_barrier
	v_mfma_f32_16x16x32_bf16 v[62:65], v[146:149], v[188:191], v[62:65]
	v_mfma_f32_16x16x32_bf16 v[58:61], v[164:167], v[188:191], v[58:61]
	v_mfma_f32_16x16x32_bf16 v[46:49], v[146:149], v[196:199], v[46:49]
	v_mfma_f32_16x16x32_bf16 v[42:45], v[164:167], v[196:199], v[42:45]
	v_mfma_f32_16x16x32_bf16 v[30:33], v[146:149], v[204:207], v[30:33]
	v_mfma_f32_16x16x32_bf16 v[26:29], v[164:167], v[204:207], v[26:29]
	v_mfma_f32_16x16x32_bf16 v[14:17], v[146:149], v[212:215], v[14:17]
	v_mfma_f32_16x16x32_bf16 v[10:13], v[164:167], v[212:215], v[10:13]
	v_mfma_f32_16x16x32_bf16 v[62:65], v[158:161], v[192:195], v[62:65]
	v_mfma_f32_16x16x32_bf16 v[58:61], v[168:171], v[192:195], v[58:61]
	v_mfma_f32_16x16x32_bf16 v[46:49], v[158:161], v[200:203], v[46:49]
	v_mfma_f32_16x16x32_bf16 v[42:45], v[168:171], v[200:203], v[42:45]
	v_mfma_f32_16x16x32_bf16 v[30:33], v[158:161], v[208:211], v[30:33]
	v_mfma_f32_16x16x32_bf16 v[26:29], v[168:171], v[208:211], v[26:29]
	v_mfma_f32_16x16x32_bf16 v[14:17], v[158:161], v[216:219], v[14:17]
	v_mfma_f32_16x16x32_bf16 v[10:13], v[168:171], v[216:219], v[10:13]
	v_mfma_f32_16x16x32_bf16 v[54:57], v[172:175], v[188:191], v[54:57]
	v_mfma_f32_16x16x32_bf16 v[50:53], v[180:183], v[188:191], v[50:53]
	v_mfma_f32_16x16x32_bf16 v[38:41], v[172:175], v[196:199], v[38:41]
	v_mfma_f32_16x16x32_bf16 v[34:37], v[180:183], v[196:199], v[34:37]
	v_mfma_f32_16x16x32_bf16 v[22:25], v[172:175], v[204:207], v[22:25]
	v_mfma_f32_16x16x32_bf16 v[18:21], v[180:183], v[204:207], v[18:21]
	v_mfma_f32_16x16x32_bf16 v[6:9], v[172:175], v[212:215], v[6:9]
	v_mfma_f32_16x16x32_bf16 v[2:5], v[180:183], v[212:215], v[2:5]
	v_mfma_f32_16x16x32_bf16 v[54:57], v[176:179], v[192:195], v[54:57]
	v_mfma_f32_16x16x32_bf16 v[50:53], v[184:187], v[192:195], v[50:53]
	v_mfma_f32_16x16x32_bf16 v[38:41], v[176:179], v[200:203], v[38:41]
	v_mfma_f32_16x16x32_bf16 v[34:37], v[184:187], v[200:203], v[34:37]
	v_mfma_f32_16x16x32_bf16 v[22:25], v[176:179], v[208:211], v[22:25]
	v_mfma_f32_16x16x32_bf16 v[18:21], v[184:187], v[208:211], v[18:21]
	v_mfma_f32_16x16x32_bf16 v[6:9], v[176:179], v[216:219], v[6:9]
	v_mfma_f32_16x16x32_bf16 v[2:5], v[184:187], v[216:219], v[2:5]
	s_setprio 0
	s_barrier
	s_add_i32 s48, 0, 0x18000
	v_add_u32_e32 v150, s48, v151
	s_add_i32 s49, 0, 0x1c000
	ds_read_b128 v[146:149], v150
	ds_read_b128 v[158:161], v150 offset:1024
	ds_read_b128 v[164:167], v150 offset:2048
	ds_read_b128 v[168:171], v150 offset:3072
	v_add_u32_e32 v150, s49, v151
	ds_read_b128 v[172:175], v150
	ds_read_b128 v[176:179], v150 offset:1024
	ds_read_b128 v[180:183], v150 offset:2048
	ds_read_b128 v[184:187], v150 offset:3072
	s_add_u32 s28, s28, 0x100000
	s_addc_u32 s29, s29, 0
	s_mov_b32 m0, s33
	v_lshl_add_u64 v[228:229], s[28:29], 0, v[130:131]
	ds_read_b128 v[188:191], v156 offset:32768
	ds_read_b128 v[192:195], v156 offset:33792
	ds_read_b128 v[196:199], v156 offset:34816
	ds_read_b128 v[200:203], v156 offset:35840
	ds_read_b128 v[204:207], v156 offset:36864
	ds_read_b128 v[208:211], v156 offset:37888
	ds_read_b128 v[212:215], v156 offset:38912
	ds_read_b128 v[216:219], v156 offset:39936
	s_mov_b32 m0, s23
	s_nop 0
	global_load_lds_dwordx4 v[224:225], off
	s_mov_b32 m0, s31
	s_nop 0
	global_load_lds_dwordx4 v[226:227], off
	s_mov_b32 m0, s33
	s_nop 0
	global_load_lds_dwordx4 v[228:229], off
	v_lshl_add_u64 v[228:229], s[28:29], 0, v[134:135]
	s_mov_b32 m0, s34
	s_nop 0
	global_load_lds_dwordx4 v[228:229], off
	s_waitcnt vmcnt(8)
	s_waitcnt lgkmcnt(0)
	s_setprio 1
	s_barrier
	v_mfma_f32_16x16x32_bf16 v[126:129], v[146:149], v[188:191], v[126:129]
	v_mfma_f32_16x16x32_bf16 v[122:125], v[164:167], v[188:191], v[122:125]
	v_mfma_f32_16x16x32_bf16 v[110:113], v[146:149], v[196:199], v[110:113]
	v_mfma_f32_16x16x32_bf16 v[106:109], v[164:167], v[196:199], v[106:109]
	v_mfma_f32_16x16x32_bf16 v[94:97], v[146:149], v[204:207], v[94:97]
	v_mfma_f32_16x16x32_bf16 v[90:93], v[164:167], v[204:207], v[90:93]
	v_mfma_f32_16x16x32_bf16 v[78:81], v[146:149], v[212:215], v[78:81]
	v_mfma_f32_16x16x32_bf16 v[74:77], v[164:167], v[212:215], v[74:77]
	v_mfma_f32_16x16x32_bf16 v[126:129], v[158:161], v[192:195], v[126:129]
	v_mfma_f32_16x16x32_bf16 v[122:125], v[168:171], v[192:195], v[122:125]
	v_mfma_f32_16x16x32_bf16 v[110:113], v[158:161], v[200:203], v[110:113]
	v_mfma_f32_16x16x32_bf16 v[106:109], v[168:171], v[200:203], v[106:109]
	v_mfma_f32_16x16x32_bf16 v[94:97], v[158:161], v[208:211], v[94:97]
	v_mfma_f32_16x16x32_bf16 v[90:93], v[168:171], v[208:211], v[90:93]
	v_mfma_f32_16x16x32_bf16 v[78:81], v[158:161], v[216:219], v[78:81]
	v_mfma_f32_16x16x32_bf16 v[74:77], v[168:171], v[216:219], v[74:77]
	v_mfma_f32_16x16x32_bf16 v[118:121], v[172:175], v[188:191], v[118:121]
	v_mfma_f32_16x16x32_bf16 v[114:117], v[180:183], v[188:191], v[114:117]
	v_mfma_f32_16x16x32_bf16 v[102:105], v[172:175], v[196:199], v[102:105]
	v_mfma_f32_16x16x32_bf16 v[98:101], v[180:183], v[196:199], v[98:101]
	v_mfma_f32_16x16x32_bf16 v[86:89], v[172:175], v[204:207], v[86:89]
	v_mfma_f32_16x16x32_bf16 v[82:85], v[180:183], v[204:207], v[82:85]
	v_mfma_f32_16x16x32_bf16 v[70:73], v[172:175], v[212:215], v[70:73]
	v_mfma_f32_16x16x32_bf16 v[66:69], v[180:183], v[212:215], v[66:69]
	v_mfma_f32_16x16x32_bf16 v[118:121], v[176:179], v[192:195], v[118:121]
	v_mfma_f32_16x16x32_bf16 v[114:117], v[184:187], v[192:195], v[114:117]
	v_mfma_f32_16x16x32_bf16 v[102:105], v[176:179], v[200:203], v[102:105]
	v_mfma_f32_16x16x32_bf16 v[98:101], v[184:187], v[200:203], v[98:101]
	v_mfma_f32_16x16x32_bf16 v[86:89], v[176:179], v[208:211], v[86:89]
	v_mfma_f32_16x16x32_bf16 v[82:85], v[184:187], v[208:211], v[82:85]
	v_mfma_f32_16x16x32_bf16 v[70:73], v[176:179], v[216:219], v[70:73]
	v_mfma_f32_16x16x32_bf16 v[66:69], v[184:187], v[216:219], v[66:69]
	s_setprio 0
	s_barrier
	s_add_i32 s28, s48, s30
	v_lshl_add_u64 v[220:221], v[220:221], 0, s[8:9]
	s_mov_b32 m0, s28
	ds_read_b128 v[188:191], v156 offset:49152
	ds_read_b128 v[192:195], v156 offset:50176
	ds_read_b128 v[196:199], v156 offset:51200
	ds_read_b128 v[200:203], v156 offset:52224
	ds_read_b128 v[204:207], v156 offset:53248
	ds_read_b128 v[208:211], v156 offset:54272
	ds_read_b128 v[212:215], v156 offset:55296
	ds_read_b128 v[216:219], v156 offset:56320
	global_load_lds_dwordx4 v[220:221], off
	s_add_i32 m0, s28, 0x2000
	s_add_u32 s26, s26, 0x100080
	v_lshl_add_u64 v[220:221], v[222:223], 0, s[8:9]
	s_addc_u32 s27, s27, 0
	s_add_i32 s28, s49, s30
	global_load_lds_dwordx4 v[220:221], off
	v_lshl_add_u64 v[220:221], s[26:27], 0, v[132:133]
	s_mov_b32 m0, s28
	s_nop 0
	global_load_lds_dwordx4 v[220:221], off
	v_lshl_add_u64 v[220:221], s[26:27], 0, v[136:137]
	s_add_i32 m0, s28, 0x2000
	s_nop 0
	global_load_lds_dwordx4 v[220:221], off
	v_lshl_add_u64 v[224:225], v[224:225], 0, s[8:9]
	v_lshl_add_u64 v[226:227], v[226:227], 0, s[8:9]
	s_waitcnt vmcnt(6)
	s_waitcnt lgkmcnt(0)
	s_setprio 1
	s_barrier
	v_mfma_f32_16x16x32_bf16 v[62:65], v[146:149], v[188:191], v[62:65]
	v_mfma_f32_16x16x32_bf16 v[58:61], v[164:167], v[188:191], v[58:61]
	v_mfma_f32_16x16x32_bf16 v[46:49], v[146:149], v[196:199], v[46:49]
	v_mfma_f32_16x16x32_bf16 v[42:45], v[164:167], v[196:199], v[42:45]
	v_mfma_f32_16x16x32_bf16 v[30:33], v[146:149], v[204:207], v[30:33]
	v_mfma_f32_16x16x32_bf16 v[26:29], v[164:167], v[204:207], v[26:29]
	v_mfma_f32_16x16x32_bf16 v[14:17], v[146:149], v[212:215], v[14:17]
	v_mfma_f32_16x16x32_bf16 v[10:13], v[164:167], v[212:215], v[10:13]
	v_mfma_f32_16x16x32_bf16 v[62:65], v[158:161], v[192:195], v[62:65]
	v_mfma_f32_16x16x32_bf16 v[58:61], v[168:171], v[192:195], v[58:61]
	v_mfma_f32_16x16x32_bf16 v[46:49], v[158:161], v[200:203], v[46:49]
	v_mfma_f32_16x16x32_bf16 v[42:45], v[168:171], v[200:203], v[42:45]
	v_mfma_f32_16x16x32_bf16 v[30:33], v[158:161], v[208:211], v[30:33]
	v_mfma_f32_16x16x32_bf16 v[26:29], v[168:171], v[208:211], v[26:29]
	v_mfma_f32_16x16x32_bf16 v[14:17], v[158:161], v[216:219], v[14:17]
	v_mfma_f32_16x16x32_bf16 v[10:13], v[168:171], v[216:219], v[10:13]
	v_mfma_f32_16x16x32_bf16 v[54:57], v[172:175], v[188:191], v[54:57]
	v_mfma_f32_16x16x32_bf16 v[50:53], v[180:183], v[188:191], v[50:53]
	v_mfma_f32_16x16x32_bf16 v[38:41], v[172:175], v[196:199], v[38:41]
	v_mfma_f32_16x16x32_bf16 v[34:37], v[180:183], v[196:199], v[34:37]
	v_mfma_f32_16x16x32_bf16 v[22:25], v[172:175], v[204:207], v[22:25]
	v_mfma_f32_16x16x32_bf16 v[18:21], v[180:183], v[204:207], v[18:21]
	v_mfma_f32_16x16x32_bf16 v[6:9], v[172:175], v[212:215], v[6:9]
	v_mfma_f32_16x16x32_bf16 v[2:5], v[180:183], v[212:215], v[2:5]
	v_mfma_f32_16x16x32_bf16 v[54:57], v[176:179], v[192:195], v[54:57]
	v_mfma_f32_16x16x32_bf16 v[50:53], v[184:187], v[192:195], v[50:53]
	v_mfma_f32_16x16x32_bf16 v[38:41], v[176:179], v[200:203], v[38:41]
	v_mfma_f32_16x16x32_bf16 v[34:37], v[184:187], v[200:203], v[34:37]
	v_mfma_f32_16x16x32_bf16 v[22:25], v[176:179], v[208:211], v[22:25]
	v_mfma_f32_16x16x32_bf16 v[18:21], v[184:187], v[208:211], v[18:21]
	v_mfma_f32_16x16x32_bf16 v[6:9], v[176:179], v[216:219], v[6:9]
	v_mfma_f32_16x16x32_bf16 v[2:5], v[184:187], v[216:219], v[2:5]
	s_setprio 0
	s_barrier
	s_add_i32 s47, s47, 2
	s_mov_b32 s32, 1
	s_add_u32 s24, s24, 0x100
	s_addc_u32 s25, s25, 0
	s_add_u32 s45, s45, 0x100
	s_addc_u32 s46, s46, 0
	s_cmp_gt_u32 s47, 61
	s_cbranch_scc0 .LBB0_820
	s_and_b64 vcc, exec, s[10:11]
	s_cbranch_vccz .LBB0_823
	s_barrier

.Lrebal_skip_978:
	s_add_i32 m0, s28, 0xc000
	s_nop 0
	global_load_lds_dwordx4 v[146:147], off
	v_lshl_add_u64 v[146:147], s[20:21], 0, v[140:141]
	s_add_i32 m0, s28, 0xe000
	s_nop 0
	global_load_lds_dwordx4 v[146:147], off
	s_waitcnt vmcnt(8)
	s_waitcnt lgkmcnt(0)
	s_setprio 1
	s_barrier
	v_mfma_f32_16x16x32_bf16 v[126:129], v[154:157], v[188:191], v[126:129]
	v_mfma_f32_16x16x32_bf16 v[122:125], v[164:167], v[188:191], v[122:125]
	v_mfma_f32_16x16x32_bf16 v[118:121], v[154:157], v[196:199], v[118:121]
	v_mfma_f32_16x16x32_bf16 v[110:113], v[164:167], v[196:199], v[110:113]
	v_mfma_f32_16x16x32_bf16 v[102:105], v[154:157], v[204:207], v[102:105]
	v_mfma_f32_16x16x32_bf16 v[94:97], v[164:167], v[204:207], v[94:97]
	v_mfma_f32_16x16x32_bf16 v[82:85], v[154:157], v[212:215], v[82:85]
	v_mfma_f32_16x16x32_bf16 v[74:77], v[164:167], v[212:215], v[74:77]
	v_mfma_f32_16x16x32_bf16 v[126:129], v[158:161], v[192:195], v[126:129]
	v_mfma_f32_16x16x32_bf16 v[122:125], v[168:171], v[192:195], v[122:125]
	v_mfma_f32_16x16x32_bf16 v[118:121], v[158:161], v[200:203], v[118:121]
	v_mfma_f32_16x16x32_bf16 v[110:113], v[168:171], v[200:203], v[110:113]
	v_mfma_f32_16x16x32_bf16 v[102:105], v[158:161], v[208:211], v[102:105]
	v_mfma_f32_16x16x32_bf16 v[94:97], v[168:171], v[208:211], v[94:97]
	v_mfma_f32_16x16x32_bf16 v[82:85], v[158:161], v[216:219], v[82:85]
	v_mfma_f32_16x16x32_bf16 v[74:77], v[168:171], v[216:219], v[74:77]
	v_mfma_f32_16x16x32_bf16 v[114:117], v[172:175], v[188:191], v[114:117]
	v_mfma_f32_16x16x32_bf16 v[106:109], v[180:183], v[188:191], v[106:109]
	v_mfma_f32_16x16x32_bf16 v[98:101], v[172:175], v[196:199], v[98:101]
	v_mfma_f32_16x16x32_bf16 v[90:93], v[180:183], v[196:199], v[90:93]
	v_mfma_f32_16x16x32_bf16 v[86:89], v[172:175], v[204:207], v[86:89]
	v_mfma_f32_16x16x32_bf16 v[78:81], v[180:183], v[204:207], v[78:81]
	v_mfma_f32_16x16x32_bf16 v[70:73], v[172:175], v[212:215], v[70:73]
	v_mfma_f32_16x16x32_bf16 v[66:69], v[180:183], v[212:215], v[66:69]
	v_mfma_f32_16x16x32_bf16 v[114:117], v[176:179], v[192:195], v[114:117]
	v_mfma_f32_16x16x32_bf16 v[106:109], v[184:187], v[192:195], v[106:109]
	v_mfma_f32_16x16x32_bf16 v[98:101], v[176:179], v[200:203], v[98:101]
	v_mfma_f32_16x16x32_bf16 v[90:93], v[184:187], v[200:203], v[90:93]
	v_mfma_f32_16x16x32_bf16 v[86:89], v[176:179], v[208:211], v[86:89]
	v_mfma_f32_16x16x32_bf16 v[78:81], v[184:187], v[208:211], v[78:81]
	v_mfma_f32_16x16x32_bf16 v[70:73], v[176:179], v[216:219], v[70:73]
	v_mfma_f32_16x16x32_bf16 v[66:69], v[184:187], v[216:219], v[66:69]
	s_setprio 0
	s_barrier
	s_add_i32 s50, s37, s27
	v_lshl_add_u64 v[146:147], s[22:23], 0, v[132:133]
	s_mov_b32 m0, s50
	ds_read_b128 v[188:191], v152 offset:16384
	ds_read_b128 v[192:195], v152 offset:17408
	ds_read_b128 v[196:199], v152 offset:18432
	ds_read_b128 v[200:203], v152 offset:19456
	ds_read_b128 v[204:207], v152 offset:20480
	ds_read_b128 v[208:211], v152 offset:21504
	ds_read_b128 v[212:215], v152 offset:22528
	ds_read_b128 v[216:219], v152 offset:23552
	global_load_lds_dwordx4 v[146:147], off
	s_add_i32 m0, s50, 0x2000
	s_add_u32 s50, s22, 0x2b0000
	v_lshl_add_u64 v[220:221], s[22:23], 0, v[136:137]
	s_addc_u32 s51, s23, 0
	s_add_i32 s52, s38, s27
	global_load_lds_dwordx4 v[220:221], off
	v_lshl_add_u64 v[222:223], s[50:51], 0, v[132:133]
	s_mov_b32 m0, s52
	v_lshl_add_u64 v[224:225], s[24:25], 0, v[134:135]
	global_load_lds_dwordx4 v[222:223], off
	v_lshl_add_u64 v[222:223], s[50:51], 0, v[136:137]
	s_add_i32 m0, s52, 0x2000
	s_nop 0
	global_load_lds_dwordx4 v[222:223], off
	v_lshl_add_u64 v[222:223], s[24:25], 0, v[130:131]
	s_waitcnt vmcnt(6)
	s_waitcnt lgkmcnt(0)
	s_setprio 1
	s_barrier
	v_mfma_f32_16x16x32_bf16 v[62:65], v[154:157], v[188:191], v[62:65]
	v_mfma_f32_16x16x32_bf16 v[58:61], v[164:167], v[188:191], v[58:61]
	v_mfma_f32_16x16x32_bf16 v[54:57], v[154:157], v[196:199], v[54:57]
	v_mfma_f32_16x16x32_bf16 v[46:49], v[164:167], v[196:199], v[46:49]
	v_mfma_f32_16x16x32_bf16 v[38:41], v[154:157], v[204:207], v[38:41]
	v_mfma_f32_16x16x32_bf16 v[30:33], v[164:167], v[204:207], v[30:33]
	v_mfma_f32_16x16x32_bf16 v[22:25], v[154:157], v[212:215], v[22:25]
	v_mfma_f32_16x16x32_bf16 v[14:17], v[164:167], v[212:215], v[14:17]
	v_mfma_f32_16x16x32_bf16 v[62:65], v[158:161], v[192:195], v[62:65]
	v_mfma_f32_16x16x32_bf16 v[58:61], v[168:171], v[192:195], v[58:61]
	v_mfma_f32_16x16x32_bf16 v[54:57], v[158:161], v[200:203], v[54:57]
	v_mfma_f32_16x16x32_bf16 v[46:49], v[168:171], v[200:203], v[46:49]
	v_mfma_f32_16x16x32_bf16 v[38:41], v[158:161], v[208:211], v[38:41]
	v_mfma_f32_16x16x32_bf16 v[30:33], v[168:171], v[208:211], v[30:33]
	v_mfma_f32_16x16x32_bf16 v[22:25], v[158:161], v[216:219], v[22:25]
	v_mfma_f32_16x16x32_bf16 v[14:17], v[168:171], v[216:219], v[14:17]
	v_mfma_f32_16x16x32_bf16 v[50:53], v[172:175], v[188:191], v[50:53]
	v_mfma_f32_16x16x32_bf16 v[42:45], v[180:183], v[188:191], v[42:45]
	v_mfma_f32_16x16x32_bf16 v[34:37], v[172:175], v[196:199], v[34:37]
	v_mfma_f32_16x16x32_bf16 v[26:29], v[180:183], v[196:199], v[26:29]
	v_mfma_f32_16x16x32_bf16 v[18:21], v[172:175], v[204:207], v[18:21]
	v_mfma_f32_16x16x32_bf16 v[10:13], v[180:183], v[204:207], v[10:13]
	v_mfma_f32_16x16x32_bf16 v[6:9], v[172:175], v[212:215], v[6:9]
	v_mfma_f32_16x16x32_bf16 v[2:5], v[180:183], v[212:215], v[2:5]
	v_mfma_f32_16x16x32_bf16 v[50:53], v[176:179], v[192:195], v[50:53]
	v_mfma_f32_16x16x32_bf16 v[42:45], v[184:187], v[192:195], v[42:45]
	v_mfma_f32_16x16x32_bf16 v[34:37], v[176:179], v[200:203], v[34:37]
	v_mfma_f32_16x16x32_bf16 v[26:29], v[184:187], v[200:203], v[26:29]
	v_mfma_f32_16x16x32_bf16 v[18:21], v[176:179], v[208:211], v[18:21]
	v_mfma_f32_16x16x32_bf16 v[10:13], v[184:187], v[208:211], v[10:13]
	v_mfma_f32_16x16x32_bf16 v[6:9], v[176:179], v[216:219], v[6:9]
	v_mfma_f32_16x16x32_bf16 v[2:5], v[184:187], v[216:219], v[2:5]
	s_setprio 0
	s_barrier
	s_add_i32 s50, 0, 0x18000
	v_add_u32_e32 v153, s50, v148
	s_add_i32 s51, 0, 0x1c000
	ds_read_b128 v[154:157], v153
	ds_read_b128 v[158:161], v153 offset:1024
	ds_read_b128 v[164:167], v153 offset:2048
	ds_read_b128 v[168:171], v153 offset:3072
	v_add_u32_e32 v153, s51, v148
	ds_read_b128 v[172:175], v153
	ds_read_b128 v[176:179], v153 offset:1024
	ds_read_b128 v[180:183], v153 offset:2048
	ds_read_b128 v[184:187], v153 offset:3072
	s_add_u32 s24, s24, 0x2b0000
	s_addc_u32 s25, s25, 0
	s_mov_b32 m0, s30
	v_lshl_add_u64 v[226:227], s[24:25], 0, v[130:131]
	ds_read_b128 v[188:191], v152 offset:32768
	ds_read_b128 v[192:195], v152 offset:33792
	ds_read_b128 v[196:199], v152 offset:34816
	ds_read_b128 v[200:203], v152 offset:35840
	ds_read_b128 v[204:207], v152 offset:36864
	ds_read_b128 v[208:211], v152 offset:37888
	ds_read_b128 v[212:215], v152 offset:38912
	ds_read_b128 v[216:219], v152 offset:39936
	s_mov_b32 m0, s28
	s_nop 0
	global_load_lds_dwordx4 v[222:223], off
	s_mov_b32 m0, s29
	s_nop 0
	global_load_lds_dwordx4 v[224:225], off
	s_mov_b32 m0, s30
	s_nop 0
	global_load_lds_dwordx4 v[226:227], off
	v_lshl_add_u64 v[226:227], s[24:25], 0, v[134:135]
	s_mov_b32 m0, s31
	s_nop 0
	global_load_lds_dwordx4 v[226:227], off
	s_waitcnt vmcnt(8)
	s_waitcnt lgkmcnt(0)
	s_setprio 1
	s_barrier
	v_mfma_f32_16x16x32_bf16 v[126:129], v[154:157], v[188:191], v[126:129]
	v_mfma_f32_16x16x32_bf16 v[122:125], v[164:167], v[188:191], v[122:125]
	v_mfma_f32_16x16x32_bf16 v[118:121], v[154:157], v[196:199], v[118:121]
	v_mfma_f32_16x16x32_bf16 v[110:113], v[164:167], v[196:199], v[110:113]
	v_mfma_f32_16x16x32_bf16 v[102:105], v[154:157], v[204:207], v[102:105]
	v_mfma_f32_16x16x32_bf16 v[94:97], v[164:167], v[204:207], v[94:97]
	v_mfma_f32_16x16x32_bf16 v[82:85], v[154:157], v[212:215], v[82:85]
	v_mfma_f32_16x16x32_bf16 v[74:77], v[164:167], v[212:215], v[74:77]
	v_mfma_f32_16x16x32_bf16 v[126:129], v[158:161], v[192:195], v[126:129]
	v_mfma_f32_16x16x32_bf16 v[122:125], v[168:171], v[192:195], v[122:125]
	v_mfma_f32_16x16x32_bf16 v[118:121], v[158:161], v[200:203], v[118:121]
	v_mfma_f32_16x16x32_bf16 v[110:113], v[168:171], v[200:203], v[110:113]
	v_mfma_f32_16x16x32_bf16 v[102:105], v[158:161], v[208:211], v[102:105]
	v_mfma_f32_16x16x32_bf16 v[94:97], v[168:171], v[208:211], v[94:97]
	v_mfma_f32_16x16x32_bf16 v[82:85], v[158:161], v[216:219], v[82:85]
	v_mfma_f32_16x16x32_bf16 v[74:77], v[168:171], v[216:219], v[74:77]
	v_mfma_f32_16x16x32_bf16 v[114:117], v[172:175], v[188:191], v[114:117]
	v_mfma_f32_16x16x32_bf16 v[106:109], v[180:183], v[188:191], v[106:109]
	v_mfma_f32_16x16x32_bf16 v[98:101], v[172:175], v[196:199], v[98:101]
	v_mfma_f32_16x16x32_bf16 v[90:93], v[180:183], v[196:199], v[90:93]
	v_mfma_f32_16x16x32_bf16 v[86:89], v[172:175], v[204:207], v[86:89]
	v_mfma_f32_16x16x32_bf16 v[78:81], v[180:183], v[204:207], v[78:81]
	v_mfma_f32_16x16x32_bf16 v[70:73], v[172:175], v[212:215], v[70:73]
	v_mfma_f32_16x16x32_bf16 v[66:69], v[180:183], v[212:215], v[66:69]
	v_mfma_f32_16x16x32_bf16 v[114:117], v[176:179], v[192:195], v[114:117]
	v_mfma_f32_16x16x32_bf16 v[106:109], v[184:187], v[192:195], v[106:109]
	v_mfma_f32_16x16x32_bf16 v[98:101], v[176:179], v[200:203], v[98:101]
	v_mfma_f32_16x16x32_bf16 v[90:93], v[184:187], v[200:203], v[90:93]
	v_mfma_f32_16x16x32_bf16 v[86:89], v[176:179], v[208:211], v[86:89]
	v_mfma_f32_16x16x32_bf16 v[78:81], v[184:187], v[208:211], v[78:81]
	v_mfma_f32_16x16x32_bf16 v[70:73], v[176:179], v[216:219], v[70:73]
	v_mfma_f32_16x16x32_bf16 v[66:69], v[184:187], v[216:219], v[66:69]
	s_setprio 0
	s_barrier
	s_add_i32 s24, s50, s27
	v_lshl_add_u64 v[146:147], v[146:147], 0, s[8:9]
	s_mov_b32 m0, s24
	ds_read_b128 v[188:191], v152 offset:49152
	ds_read_b128 v[192:195], v152 offset:50176
	ds_read_b128 v[196:199], v152 offset:51200
	ds_read_b128 v[200:203], v152 offset:52224
	ds_read_b128 v[204:207], v152 offset:53248
	ds_read_b128 v[208:211], v152 offset:54272
	ds_read_b128 v[212:215], v152 offset:55296
	ds_read_b128 v[216:219], v152 offset:56320
	global_load_lds_dwordx4 v[146:147], off
	s_add_i32 m0, s24, 0x2000
	s_add_u32 s22, s22, 0x2b0080
	v_lshl_add_u64 v[146:147], v[220:221], 0, s[8:9]
	s_addc_u32 s23, s23, 0
	s_add_i32 s24, s51, s27
	global_load_lds_dwordx4 v[146:147], off
	v_lshl_add_u64 v[146:147], s[22:23], 0, v[132:133]
	s_mov_b32 m0, s24
	s_nop 0
	global_load_lds_dwordx4 v[146:147], off
	v_lshl_add_u64 v[146:147], s[22:23], 0, v[136:137]
	s_add_i32 m0, s24, 0x2000
	s_nop 0
	global_load_lds_dwordx4 v[146:147], off
	v_lshl_add_u64 v[222:223], v[222:223], 0, s[8:9]
	v_lshl_add_u64 v[224:225], v[224:225], 0, s[8:9]
	s_waitcnt vmcnt(6)
	s_waitcnt lgkmcnt(0)
	s_setprio 1
	s_barrier
	v_mfma_f32_16x16x32_bf16 v[62:65], v[154:157], v[188:191], v[62:65]
	v_mfma_f32_16x16x32_bf16 v[58:61], v[164:167], v[188:191], v[58:61]
	v_mfma_f32_16x16x32_bf16 v[54:57], v[154:157], v[196:199], v[54:57]
	v_mfma_f32_16x16x32_bf16 v[46:49], v[164:167], v[196:199], v[46:49]
	v_mfma_f32_16x16x32_bf16 v[38:41], v[154:157], v[204:207], v[38:41]
	v_mfma_f32_16x16x32_bf16 v[30:33], v[164:167], v[204:207], v[30:33]
	v_mfma_f32_16x16x32_bf16 v[22:25], v[154:157], v[212:215], v[22:25]
	v_mfma_f32_16x16x32_bf16 v[14:17], v[164:167], v[212:215], v[14:17]
	v_mfma_f32_16x16x32_bf16 v[62:65], v[158:161], v[192:195], v[62:65]
	v_mfma_f32_16x16x32_bf16 v[58:61], v[168:171], v[192:195], v[58:61]
	v_mfma_f32_16x16x32_bf16 v[54:57], v[158:161], v[200:203], v[54:57]
	v_mfma_f32_16x16x32_bf16 v[46:49], v[168:171], v[200:203], v[46:49]
	v_mfma_f32_16x16x32_bf16 v[38:41], v[158:161], v[208:211], v[38:41]
	v_mfma_f32_16x16x32_bf16 v[30:33], v[168:171], v[208:211], v[30:33]
	v_mfma_f32_16x16x32_bf16 v[22:25], v[158:161], v[216:219], v[22:25]
	v_mfma_f32_16x16x32_bf16 v[14:17], v[168:171], v[216:219], v[14:17]
	v_mfma_f32_16x16x32_bf16 v[50:53], v[172:175], v[188:191], v[50:53]
	v_mfma_f32_16x16x32_bf16 v[42:45], v[180:183], v[188:191], v[42:45]
	v_mfma_f32_16x16x32_bf16 v[34:37], v[172:175], v[196:199], v[34:37]
	v_mfma_f32_16x16x32_bf16 v[26:29], v[180:183], v[196:199], v[26:29]
	v_mfma_f32_16x16x32_bf16 v[18:21], v[172:175], v[204:207], v[18:21]
	v_mfma_f32_16x16x32_bf16 v[10:13], v[180:183], v[204:207], v[10:13]
	v_mfma_f32_16x16x32_bf16 v[6:9], v[172:175], v[212:215], v[6:9]
	v_mfma_f32_16x16x32_bf16 v[2:5], v[180:183], v[212:215], v[2:5]
	v_mfma_f32_16x16x32_bf16 v[50:53], v[176:179], v[192:195], v[50:53]
	v_mfma_f32_16x16x32_bf16 v[42:45], v[184:187], v[192:195], v[42:45]
	v_mfma_f32_16x16x32_bf16 v[34:37], v[176:179], v[200:203], v[34:37]
	v_mfma_f32_16x16x32_bf16 v[26:29], v[184:187], v[200:203], v[26:29]
	v_mfma_f32_16x16x32_bf16 v[18:21], v[176:179], v[208:211], v[18:21]
	v_mfma_f32_16x16x32_bf16 v[10:13], v[184:187], v[208:211], v[10:13]
	v_mfma_f32_16x16x32_bf16 v[6:9], v[176:179], v[216:219], v[6:9]
	v_mfma_f32_16x16x32_bf16 v[2:5], v[184:187], v[216:219], v[2:5]
	s_setprio 0
	s_barrier
	s_add_i32 s49, s49, 2
	s_mov_b32 s32, 1
	s_add_u32 s20, s20, 0x100
	s_addc_u32 s21, s21, 0
	s_add_u32 s47, s47, 0x100
	s_addc_u32 s48, s48, 0
	s_cmpk_gt_u32 s49, 0xa9
	s_cbranch_scc0 .LBB0_978
	s_and_b64 vcc, exec, s[10:11]
	s_cbranch_vccz .LBB0_981
	s_barrier

.Lrebal_skip_1131:
	s_add_i32 m0, s29, 0xc000
	s_nop 0
	global_load_lds_dwordx4 v[160:161], off
	v_lshl_add_u64 v[160:161], s[30:31], 0, v[140:141]
	s_add_i32 m0, s29, 0xe000
	s_nop 0
	global_load_lds_dwordx4 v[160:161], off
	s_waitcnt vmcnt(8)
	s_waitcnt lgkmcnt(0)
	s_setprio 1
	s_barrier
	v_mfma_f32_16x16x32_bf16 v[126:129], v[146:149], v[188:191], v[126:129]
	v_mfma_f32_16x16x32_bf16 v[122:125], v[164:167], v[188:191], v[122:125]
	v_mfma_f32_16x16x32_bf16 v[110:113], v[146:149], v[196:199], v[110:113]
	v_mfma_f32_16x16x32_bf16 v[106:109], v[164:167], v[196:199], v[106:109]
	v_mfma_f32_16x16x32_bf16 v[94:97], v[146:149], v[204:207], v[94:97]
	v_mfma_f32_16x16x32_bf16 v[90:93], v[164:167], v[204:207], v[90:93]
	v_mfma_f32_16x16x32_bf16 v[78:81], v[146:149], v[212:215], v[78:81]
	v_mfma_f32_16x16x32_bf16 v[74:77], v[164:167], v[212:215], v[74:77]
	v_mfma_f32_16x16x32_bf16 v[126:129], v[150:153], v[192:195], v[126:129]
	v_mfma_f32_16x16x32_bf16 v[122:125], v[168:171], v[192:195], v[122:125]
	v_mfma_f32_16x16x32_bf16 v[110:113], v[150:153], v[200:203], v[110:113]
	v_mfma_f32_16x16x32_bf16 v[106:109], v[168:171], v[200:203], v[106:109]
	v_mfma_f32_16x16x32_bf16 v[94:97], v[150:153], v[208:211], v[94:97]
	v_mfma_f32_16x16x32_bf16 v[90:93], v[168:171], v[208:211], v[90:93]
	v_mfma_f32_16x16x32_bf16 v[78:81], v[150:153], v[216:219], v[78:81]
	v_mfma_f32_16x16x32_bf16 v[74:77], v[168:171], v[216:219], v[74:77]
	v_mfma_f32_16x16x32_bf16 v[118:121], v[172:175], v[188:191], v[118:121]
	v_mfma_f32_16x16x32_bf16 v[114:117], v[180:183], v[188:191], v[114:117]
	v_mfma_f32_16x16x32_bf16 v[102:105], v[172:175], v[196:199], v[102:105]
	v_mfma_f32_16x16x32_bf16 v[98:101], v[180:183], v[196:199], v[98:101]
	v_mfma_f32_16x16x32_bf16 v[86:89], v[172:175], v[204:207], v[86:89]
	v_mfma_f32_16x16x32_bf16 v[82:85], v[180:183], v[204:207], v[82:85]
	v_mfma_f32_16x16x32_bf16 v[70:73], v[172:175], v[212:215], v[70:73]
	v_mfma_f32_16x16x32_bf16 v[66:69], v[180:183], v[212:215], v[66:69]
	v_mfma_f32_16x16x32_bf16 v[118:121], v[176:179], v[192:195], v[118:121]
	v_mfma_f32_16x16x32_bf16 v[114:117], v[184:187], v[192:195], v[114:117]
	v_mfma_f32_16x16x32_bf16 v[102:105], v[176:179], v[200:203], v[102:105]
	v_mfma_f32_16x16x32_bf16 v[98:101], v[184:187], v[200:203], v[98:101]
	v_mfma_f32_16x16x32_bf16 v[86:89], v[176:179], v[208:211], v[86:89]
	v_mfma_f32_16x16x32_bf16 v[82:85], v[184:187], v[208:211], v[82:85]
	v_mfma_f32_16x16x32_bf16 v[70:73], v[176:179], v[216:219], v[70:73]
	v_mfma_f32_16x16x32_bf16 v[66:69], v[184:187], v[216:219], v[66:69]
	s_setprio 0
	s_barrier
	s_add_i32 s54, s46, s38
	v_lshl_add_u64 v[160:161], s[34:35], 0, v[132:133]
	s_mov_b32 m0, s54
	ds_read_b128 v[188:191], v158 offset:16384
	ds_read_b128 v[192:195], v158 offset:17408
	ds_read_b128 v[196:199], v158 offset:18432
	ds_read_b128 v[200:203], v158 offset:19456
	ds_read_b128 v[204:207], v158 offset:20480
	ds_read_b128 v[208:211], v158 offset:21504
	ds_read_b128 v[212:215], v158 offset:22528
	ds_read_b128 v[216:219], v158 offset:23552
	global_load_lds_dwordx4 v[160:161], off
	s_add_i32 m0, s54, 0x2000
	s_add_u32 s54, s34, 0x100000
	v_lshl_add_u64 v[220:221], s[34:35], 0, v[136:137]
	s_addc_u32 s55, s35, 0
	s_add_i32 s56, s47, s38
	global_load_lds_dwordx4 v[220:221], off
	v_lshl_add_u64 v[222:223], s[54:55], 0, v[132:133]
	s_mov_b32 m0, s56
	v_lshl_add_u64 v[224:225], s[36:37], 0, v[134:135]
	global_load_lds_dwordx4 v[222:223], off
	v_lshl_add_u64 v[222:223], s[54:55], 0, v[136:137]
	s_add_i32 m0, s56, 0x2000
	s_nop 0
	global_load_lds_dwordx4 v[222:223], off
	v_lshl_add_u64 v[222:223], s[36:37], 0, v[130:131]
	s_waitcnt vmcnt(6)
	s_waitcnt lgkmcnt(0)
	s_setprio 1
	s_barrier
	v_mfma_f32_16x16x32_bf16 v[62:65], v[146:149], v[188:191], v[62:65]
	v_mfma_f32_16x16x32_bf16 v[58:61], v[164:167], v[188:191], v[58:61]
	v_mfma_f32_16x16x32_bf16 v[46:49], v[146:149], v[196:199], v[46:49]
	v_mfma_f32_16x16x32_bf16 v[42:45], v[164:167], v[196:199], v[42:45]
	v_mfma_f32_16x16x32_bf16 v[30:33], v[146:149], v[204:207], v[30:33]
	v_mfma_f32_16x16x32_bf16 v[26:29], v[164:167], v[204:207], v[26:29]
	v_mfma_f32_16x16x32_bf16 v[14:17], v[146:149], v[212:215], v[14:17]
	v_mfma_f32_16x16x32_bf16 v[10:13], v[164:167], v[212:215], v[10:13]
	v_mfma_f32_16x16x32_bf16 v[62:65], v[150:153], v[192:195], v[62:65]
	v_mfma_f32_16x16x32_bf16 v[58:61], v[168:171], v[192:195], v[58:61]
	v_mfma_f32_16x16x32_bf16 v[46:49], v[150:153], v[200:203], v[46:49]
	v_mfma_f32_16x16x32_bf16 v[42:45], v[168:171], v[200:203], v[42:45]
	v_mfma_f32_16x16x32_bf16 v[30:33], v[150:153], v[208:211], v[30:33]
	v_mfma_f32_16x16x32_bf16 v[26:29], v[168:171], v[208:211], v[26:29]
	v_mfma_f32_16x16x32_bf16 v[14:17], v[150:153], v[216:219], v[14:17]
	v_mfma_f32_16x16x32_bf16 v[10:13], v[168:171], v[216:219], v[10:13]
	v_mfma_f32_16x16x32_bf16 v[54:57], v[172:175], v[188:191], v[54:57]
	v_mfma_f32_16x16x32_bf16 v[50:53], v[180:183], v[188:191], v[50:53]
	v_mfma_f32_16x16x32_bf16 v[38:41], v[172:175], v[196:199], v[38:41]
	v_mfma_f32_16x16x32_bf16 v[34:37], v[180:183], v[196:199], v[34:37]
	v_mfma_f32_16x16x32_bf16 v[22:25], v[172:175], v[204:207], v[22:25]
	v_mfma_f32_16x16x32_bf16 v[18:21], v[180:183], v[204:207], v[18:21]
	v_mfma_f32_16x16x32_bf16 v[6:9], v[172:175], v[212:215], v[6:9]
	v_mfma_f32_16x16x32_bf16 v[2:5], v[180:183], v[212:215], v[2:5]
	v_mfma_f32_16x16x32_bf16 v[54:57], v[176:179], v[192:195], v[54:57]
	v_mfma_f32_16x16x32_bf16 v[50:53], v[184:187], v[192:195], v[50:53]
	v_mfma_f32_16x16x32_bf16 v[38:41], v[176:179], v[200:203], v[38:41]
	v_mfma_f32_16x16x32_bf16 v[34:37], v[184:187], v[200:203], v[34:37]
	v_mfma_f32_16x16x32_bf16 v[22:25], v[176:179], v[208:211], v[22:25]
	v_mfma_f32_16x16x32_bf16 v[18:21], v[184:187], v[208:211], v[18:21]
	v_mfma_f32_16x16x32_bf16 v[6:9], v[176:179], v[216:219], v[6:9]
	v_mfma_f32_16x16x32_bf16 v[2:5], v[184:187], v[216:219], v[2:5]
	s_setprio 0
	s_barrier
	s_add_i32 s54, 0, 0x18000
	v_add_u32_e32 v159, s54, v154
	s_add_i32 s55, 0, 0x1c000
	ds_read_b128 v[146:149], v159
	ds_read_b128 v[150:153], v159 offset:1024
	ds_read_b128 v[164:167], v159 offset:2048
	ds_read_b128 v[168:171], v159 offset:3072
	v_add_u32_e32 v159, s55, v154
	ds_read_b128 v[172:175], v159
	ds_read_b128 v[176:179], v159 offset:1024
	ds_read_b128 v[180:183], v159 offset:2048
	ds_read_b128 v[184:187], v159 offset:3072
	s_add_u32 s36, s36, 0x100000
	s_addc_u32 s37, s37, 0
	s_mov_b32 m0, s40
	v_lshl_add_u64 v[226:227], s[36:37], 0, v[130:131]
	ds_read_b128 v[188:191], v158 offset:32768
	ds_read_b128 v[192:195], v158 offset:33792
	ds_read_b128 v[196:199], v158 offset:34816
	ds_read_b128 v[200:203], v158 offset:35840
	ds_read_b128 v[204:207], v158 offset:36864
	ds_read_b128 v[208:211], v158 offset:37888
	ds_read_b128 v[212:215], v158 offset:38912
	ds_read_b128 v[216:219], v158 offset:39936
	s_mov_b32 m0, s29
	s_nop 0
	global_load_lds_dwordx4 v[222:223], off
	s_mov_b32 m0, s39
	s_nop 0
	global_load_lds_dwordx4 v[224:225], off
	s_mov_b32 m0, s40
	s_nop 0
	global_load_lds_dwordx4 v[226:227], off
	v_lshl_add_u64 v[226:227], s[36:37], 0, v[134:135]
	s_mov_b32 m0, s41
	s_nop 0
	global_load_lds_dwordx4 v[226:227], off
	s_waitcnt vmcnt(8)
	s_waitcnt lgkmcnt(0)
	s_setprio 1
	s_barrier
	v_mfma_f32_16x16x32_bf16 v[126:129], v[146:149], v[188:191], v[126:129]
	v_mfma_f32_16x16x32_bf16 v[122:125], v[164:167], v[188:191], v[122:125]
	v_mfma_f32_16x16x32_bf16 v[110:113], v[146:149], v[196:199], v[110:113]
	v_mfma_f32_16x16x32_bf16 v[106:109], v[164:167], v[196:199], v[106:109]
	v_mfma_f32_16x16x32_bf16 v[94:97], v[146:149], v[204:207], v[94:97]
	v_mfma_f32_16x16x32_bf16 v[90:93], v[164:167], v[204:207], v[90:93]
	v_mfma_f32_16x16x32_bf16 v[78:81], v[146:149], v[212:215], v[78:81]
	v_mfma_f32_16x16x32_bf16 v[74:77], v[164:167], v[212:215], v[74:77]
	v_mfma_f32_16x16x32_bf16 v[126:129], v[150:153], v[192:195], v[126:129]
	v_mfma_f32_16x16x32_bf16 v[122:125], v[168:171], v[192:195], v[122:125]
	v_mfma_f32_16x16x32_bf16 v[110:113], v[150:153], v[200:203], v[110:113]
	v_mfma_f32_16x16x32_bf16 v[106:109], v[168:171], v[200:203], v[106:109]
	v_mfma_f32_16x16x32_bf16 v[94:97], v[150:153], v[208:211], v[94:97]
	v_mfma_f32_16x16x32_bf16 v[90:93], v[168:171], v[208:211], v[90:93]
	v_mfma_f32_16x16x32_bf16 v[78:81], v[150:153], v[216:219], v[78:81]
	v_mfma_f32_16x16x32_bf16 v[74:77], v[168:171], v[216:219], v[74:77]
	v_mfma_f32_16x16x32_bf16 v[118:121], v[172:175], v[188:191], v[118:121]
	v_mfma_f32_16x16x32_bf16 v[114:117], v[180:183], v[188:191], v[114:117]
	v_mfma_f32_16x16x32_bf16 v[102:105], v[172:175], v[196:199], v[102:105]
	v_mfma_f32_16x16x32_bf16 v[98:101], v[180:183], v[196:199], v[98:101]
	v_mfma_f32_16x16x32_bf16 v[86:89], v[172:175], v[204:207], v[86:89]
	v_mfma_f32_16x16x32_bf16 v[82:85], v[180:183], v[204:207], v[82:85]
	v_mfma_f32_16x16x32_bf16 v[70:73], v[172:175], v[212:215], v[70:73]
	v_mfma_f32_16x16x32_bf16 v[66:69], v[180:183], v[212:215], v[66:69]
	v_mfma_f32_16x16x32_bf16 v[118:121], v[176:179], v[192:195], v[118:121]
	v_mfma_f32_16x16x32_bf16 v[114:117], v[184:187], v[192:195], v[114:117]
	v_mfma_f32_16x16x32_bf16 v[102:105], v[176:179], v[200:203], v[102:105]
	v_mfma_f32_16x16x32_bf16 v[98:101], v[184:187], v[200:203], v[98:101]
	v_mfma_f32_16x16x32_bf16 v[86:89], v[176:179], v[208:211], v[86:89]
	v_mfma_f32_16x16x32_bf16 v[82:85], v[184:187], v[208:211], v[82:85]
	v_mfma_f32_16x16x32_bf16 v[70:73], v[176:179], v[216:219], v[70:73]
	v_mfma_f32_16x16x32_bf16 v[66:69], v[184:187], v[216:219], v[66:69]
	s_setprio 0
	s_barrier
	s_add_i32 s36, s54, s38
	v_lshl_add_u64 v[160:161], v[160:161], 0, s[10:11]
	s_mov_b32 m0, s36
	ds_read_b128 v[188:191], v158 offset:49152
	ds_read_b128 v[192:195], v158 offset:50176
	ds_read_b128 v[196:199], v158 offset:51200
	ds_read_b128 v[200:203], v158 offset:52224
	ds_read_b128 v[204:207], v158 offset:53248
	ds_read_b128 v[208:211], v158 offset:54272
	ds_read_b128 v[212:215], v158 offset:55296
	ds_read_b128 v[216:219], v158 offset:56320
	global_load_lds_dwordx4 v[160:161], off
	s_add_i32 m0, s36, 0x2000
	s_add_u32 s34, s34, 0x100080
	v_lshl_add_u64 v[160:161], v[220:221], 0, s[10:11]
	s_addc_u32 s35, s35, 0
	s_add_i32 s36, s55, s38
	global_load_lds_dwordx4 v[160:161], off
	v_lshl_add_u64 v[160:161], s[34:35], 0, v[132:133]
	s_mov_b32 m0, s36
	s_nop 0
	global_load_lds_dwordx4 v[160:161], off
	v_lshl_add_u64 v[160:161], s[34:35], 0, v[136:137]
	s_add_i32 m0, s36, 0x2000
	s_nop 0
	global_load_lds_dwordx4 v[160:161], off
	v_lshl_add_u64 v[222:223], v[222:223], 0, s[10:11]
	v_lshl_add_u64 v[224:225], v[224:225], 0, s[10:11]
	s_waitcnt vmcnt(6)
	s_waitcnt lgkmcnt(0)
	s_setprio 1
	s_barrier
	v_mfma_f32_16x16x32_bf16 v[62:65], v[146:149], v[188:191], v[62:65]
	v_mfma_f32_16x16x32_bf16 v[58:61], v[164:167], v[188:191], v[58:61]
	v_mfma_f32_16x16x32_bf16 v[46:49], v[146:149], v[196:199], v[46:49]
	v_mfma_f32_16x16x32_bf16 v[42:45], v[164:167], v[196:199], v[42:45]
	v_mfma_f32_16x16x32_bf16 v[30:33], v[146:149], v[204:207], v[30:33]
	v_mfma_f32_16x16x32_bf16 v[26:29], v[164:167], v[204:207], v[26:29]
	v_mfma_f32_16x16x32_bf16 v[14:17], v[146:149], v[212:215], v[14:17]
	v_mfma_f32_16x16x32_bf16 v[10:13], v[164:167], v[212:215], v[10:13]
	v_mfma_f32_16x16x32_bf16 v[62:65], v[150:153], v[192:195], v[62:65]
	v_mfma_f32_16x16x32_bf16 v[58:61], v[168:171], v[192:195], v[58:61]
	v_mfma_f32_16x16x32_bf16 v[46:49], v[150:153], v[200:203], v[46:49]
	v_mfma_f32_16x16x32_bf16 v[42:45], v[168:171], v[200:203], v[42:45]
	v_mfma_f32_16x16x32_bf16 v[30:33], v[150:153], v[208:211], v[30:33]
	v_mfma_f32_16x16x32_bf16 v[26:29], v[168:171], v[208:211], v[26:29]
	v_mfma_f32_16x16x32_bf16 v[14:17], v[150:153], v[216:219], v[14:17]
	v_mfma_f32_16x16x32_bf16 v[10:13], v[168:171], v[216:219], v[10:13]
	v_mfma_f32_16x16x32_bf16 v[54:57], v[172:175], v[188:191], v[54:57]
	v_mfma_f32_16x16x32_bf16 v[50:53], v[180:183], v[188:191], v[50:53]
	v_mfma_f32_16x16x32_bf16 v[38:41], v[172:175], v[196:199], v[38:41]
	v_mfma_f32_16x16x32_bf16 v[34:37], v[180:183], v[196:199], v[34:37]
	v_mfma_f32_16x16x32_bf16 v[22:25], v[172:175], v[204:207], v[22:25]
	v_mfma_f32_16x16x32_bf16 v[18:21], v[180:183], v[204:207], v[18:21]
	v_mfma_f32_16x16x32_bf16 v[6:9], v[172:175], v[212:215], v[6:9]
	v_mfma_f32_16x16x32_bf16 v[2:5], v[180:183], v[212:215], v[2:5]
	v_mfma_f32_16x16x32_bf16 v[54:57], v[176:179], v[192:195], v[54:57]
	v_mfma_f32_16x16x32_bf16 v[50:53], v[184:187], v[192:195], v[50:53]
	v_mfma_f32_16x16x32_bf16 v[38:41], v[176:179], v[200:203], v[38:41]
	v_mfma_f32_16x16x32_bf16 v[34:37], v[184:187], v[200:203], v[34:37]
	v_mfma_f32_16x16x32_bf16 v[22:25], v[176:179], v[208:211], v[22:25]
	v_mfma_f32_16x16x32_bf16 v[18:21], v[184:187], v[208:211], v[18:21]
	v_mfma_f32_16x16x32_bf16 v[6:9], v[176:179], v[216:219], v[6:9]
	v_mfma_f32_16x16x32_bf16 v[2:5], v[184:187], v[216:219], v[2:5]
	s_setprio 0
	s_barrier
	s_add_i32 s53, s53, 2
	s_mov_b32 s32, 1
	s_add_u32 s30, s30, 0x100
	s_addc_u32 s31, s31, 0
	s_add_u32 s51, s51, 0x100
	s_addc_u32 s52, s52, 0
	s_cmp_gt_u32 s53, 61
	s_cbranch_scc0 .LBB0_1131
	s_and_b64 vcc, exec, s[12:13]
	s_cbranch_vccz .LBB0_1134
	s_barrier

.Lrebal_skip_1260:
	s_add_i32 m0, s36, 0xc000
	s_nop 0
	global_load_lds_dwordx4 v[160:161], off
	v_lshl_add_u64 v[160:161], s[26:27], 0, v[142:143]
	s_add_i32 m0, s36, 0xe000
	s_nop 0
	global_load_lds_dwordx4 v[160:161], off
	s_waitcnt vmcnt(8)
	s_waitcnt lgkmcnt(0)
	s_setprio 1
	s_barrier
	v_mfma_f32_16x16x32_bf16 v[126:129], v[148:151], v[190:193], v[126:129]
	v_mfma_f32_16x16x32_bf16 v[122:125], v[156:159], v[190:193], v[122:125]
	v_mfma_f32_16x16x32_bf16 v[110:113], v[148:151], v[198:201], v[110:113]
	v_mfma_f32_16x16x32_bf16 v[106:109], v[156:159], v[198:201], v[106:109]
	v_mfma_f32_16x16x32_bf16 v[94:97], v[148:151], v[206:209], v[94:97]
	v_mfma_f32_16x16x32_bf16 v[90:93], v[156:159], v[206:209], v[90:93]
	v_mfma_f32_16x16x32_bf16 v[86:89], v[148:151], v[214:217], v[86:89]
	v_mfma_f32_16x16x32_bf16 v[78:81], v[156:159], v[214:217], v[78:81]
	v_mfma_f32_16x16x32_bf16 v[126:129], v[152:155], v[194:197], v[126:129]
	v_mfma_f32_16x16x32_bf16 v[122:125], v[170:173], v[194:197], v[122:125]
	v_mfma_f32_16x16x32_bf16 v[110:113], v[152:155], v[202:205], v[110:113]
	v_mfma_f32_16x16x32_bf16 v[106:109], v[170:173], v[202:205], v[106:109]
	v_mfma_f32_16x16x32_bf16 v[94:97], v[152:155], v[210:213], v[94:97]
	v_mfma_f32_16x16x32_bf16 v[90:93], v[170:173], v[210:213], v[90:93]
	v_mfma_f32_16x16x32_bf16 v[86:89], v[152:155], v[218:221], v[86:89]
	v_mfma_f32_16x16x32_bf16 v[78:81], v[170:173], v[218:221], v[78:81]
	v_mfma_f32_16x16x32_bf16 v[118:121], v[174:177], v[190:193], v[118:121]
	v_mfma_f32_16x16x32_bf16 v[114:117], v[182:185], v[190:193], v[114:117]
	v_mfma_f32_16x16x32_bf16 v[102:105], v[174:177], v[198:201], v[102:105]
	v_mfma_f32_16x16x32_bf16 v[98:101], v[182:185], v[198:201], v[98:101]
	v_mfma_f32_16x16x32_bf16 v[82:85], v[174:177], v[206:209], v[82:85]
	v_mfma_f32_16x16x32_bf16 v[74:77], v[182:185], v[206:209], v[74:77]
	v_mfma_f32_16x16x32_bf16 v[70:73], v[174:177], v[214:217], v[70:73]
	v_mfma_f32_16x16x32_bf16 v[66:69], v[182:185], v[214:217], v[66:69]
	v_mfma_f32_16x16x32_bf16 v[118:121], v[178:181], v[194:197], v[118:121]
	v_mfma_f32_16x16x32_bf16 v[114:117], v[186:189], v[194:197], v[114:117]
	v_mfma_f32_16x16x32_bf16 v[102:105], v[178:181], v[202:205], v[102:105]
	v_mfma_f32_16x16x32_bf16 v[98:101], v[186:189], v[202:205], v[98:101]
	v_mfma_f32_16x16x32_bf16 v[82:85], v[178:181], v[210:213], v[82:85]
	v_mfma_f32_16x16x32_bf16 v[74:77], v[186:189], v[210:213], v[74:77]
	v_mfma_f32_16x16x32_bf16 v[70:73], v[178:181], v[218:221], v[70:73]
	v_mfma_f32_16x16x32_bf16 v[66:69], v[186:189], v[218:221], v[66:69]
	s_setprio 0
	s_barrier
	s_add_i32 s56, s44, s33
	v_lshl_add_u64 v[160:161], s[28:29], 0, v[134:135]
	s_mov_b32 m0, s56
	ds_read_b128 v[190:193], v168 offset:16384
	ds_read_b128 v[194:197], v168 offset:17408
	ds_read_b128 v[198:201], v168 offset:18432
	ds_read_b128 v[202:205], v168 offset:19456
	ds_read_b128 v[206:209], v168 offset:20480
	ds_read_b128 v[210:213], v168 offset:21504
	ds_read_b128 v[214:217], v168 offset:22528
	ds_read_b128 v[218:221], v168 offset:23552
	global_load_lds_dwordx4 v[160:161], off
	s_add_i32 m0, s56, 0x2000
	s_add_u32 s56, s28, 0x100000
	v_lshl_add_u64 v[222:223], s[28:29], 0, v[130:131]
	s_addc_u32 s57, s29, 0
	s_add_i32 s58, s45, s33
	global_load_lds_dwordx4 v[222:223], off
	v_lshl_add_u64 v[224:225], s[56:57], 0, v[134:135]
	s_mov_b32 m0, s58
	v_lshl_add_u64 v[226:227], s[30:31], 0, v[132:133]
	global_load_lds_dwordx4 v[224:225], off
	v_lshl_add_u64 v[224:225], s[56:57], 0, v[130:131]
	s_add_i32 m0, s58, 0x2000
	s_nop 0
	global_load_lds_dwordx4 v[224:225], off
	v_lshl_add_u64 v[224:225], s[30:31], 0, v[136:137]
	s_waitcnt vmcnt(6)
	s_waitcnt lgkmcnt(0)
	s_setprio 1
	s_barrier
	v_mfma_f32_16x16x32_bf16 v[62:65], v[148:151], v[190:193], v[62:65]
	v_mfma_f32_16x16x32_bf16 v[58:61], v[156:159], v[190:193], v[58:61]
	v_mfma_f32_16x16x32_bf16 v[46:49], v[148:151], v[198:201], v[46:49]
	v_mfma_f32_16x16x32_bf16 v[42:45], v[156:159], v[198:201], v[42:45]
	v_mfma_f32_16x16x32_bf16 v[30:33], v[148:151], v[206:209], v[30:33]
	v_mfma_f32_16x16x32_bf16 v[26:29], v[156:159], v[206:209], v[26:29]
	v_mfma_f32_16x16x32_bf16 v[14:17], v[148:151], v[214:217], v[14:17]
	v_mfma_f32_16x16x32_bf16 v[10:13], v[156:159], v[214:217], v[10:13]
	v_mfma_f32_16x16x32_bf16 v[62:65], v[152:155], v[194:197], v[62:65]
	v_mfma_f32_16x16x32_bf16 v[58:61], v[170:173], v[194:197], v[58:61]
	v_mfma_f32_16x16x32_bf16 v[46:49], v[152:155], v[202:205], v[46:49]
	v_mfma_f32_16x16x32_bf16 v[42:45], v[170:173], v[202:205], v[42:45]
	v_mfma_f32_16x16x32_bf16 v[30:33], v[152:155], v[210:213], v[30:33]
	v_mfma_f32_16x16x32_bf16 v[26:29], v[170:173], v[210:213], v[26:29]
	v_mfma_f32_16x16x32_bf16 v[14:17], v[152:155], v[218:221], v[14:17]
	v_mfma_f32_16x16x32_bf16 v[10:13], v[170:173], v[218:221], v[10:13]
	v_mfma_f32_16x16x32_bf16 v[54:57], v[174:177], v[190:193], v[54:57]
	v_mfma_f32_16x16x32_bf16 v[50:53], v[182:185], v[190:193], v[50:53]
	v_mfma_f32_16x16x32_bf16 v[38:41], v[174:177], v[198:201], v[38:41]
	v_mfma_f32_16x16x32_bf16 v[34:37], v[182:185], v[198:201], v[34:37]
	v_mfma_f32_16x16x32_bf16 v[22:25], v[174:177], v[206:209], v[22:25]
	v_mfma_f32_16x16x32_bf16 v[18:21], v[182:185], v[206:209], v[18:21]
	v_mfma_f32_16x16x32_bf16 v[6:9], v[174:177], v[214:217], v[6:9]
	v_mfma_f32_16x16x32_bf16 v[2:5], v[182:185], v[214:217], v[2:5]
	v_mfma_f32_16x16x32_bf16 v[54:57], v[178:181], v[194:197], v[54:57]
	v_mfma_f32_16x16x32_bf16 v[50:53], v[186:189], v[194:197], v[50:53]
	v_mfma_f32_16x16x32_bf16 v[38:41], v[178:181], v[202:205], v[38:41]
	v_mfma_f32_16x16x32_bf16 v[34:37], v[186:189], v[202:205], v[34:37]
	v_mfma_f32_16x16x32_bf16 v[22:25], v[178:181], v[210:213], v[22:25]
	v_mfma_f32_16x16x32_bf16 v[18:21], v[186:189], v[210:213], v[18:21]
	v_mfma_f32_16x16x32_bf16 v[6:9], v[178:181], v[218:221], v[6:9]
	v_mfma_f32_16x16x32_bf16 v[2:5], v[186:189], v[218:221], v[2:5]
	s_setprio 0
	s_barrier
	s_add_i32 s56, 0, 0x18000
	v_add_u32_e32 v169, s56, v164
	s_add_i32 s57, 0, 0x1c000
	ds_read_b128 v[148:151], v169
	ds_read_b128 v[152:155], v169 offset:1024
	ds_read_b128 v[156:159], v169 offset:2048
	ds_read_b128 v[170:173], v169 offset:3072
	v_add_u32_e32 v169, s57, v164
	ds_read_b128 v[174:177], v169
	ds_read_b128 v[178:181], v169 offset:1024
	ds_read_b128 v[182:185], v169 offset:2048
	ds_read_b128 v[186:189], v169 offset:3072
	s_add_u32 s30, s30, 0x100000
	s_addc_u32 s31, s31, 0
	s_mov_b32 m0, s38
	v_lshl_add_u64 v[228:229], s[30:31], 0, v[136:137]
	ds_read_b128 v[190:193], v168 offset:32768
	ds_read_b128 v[194:197], v168 offset:33792
	ds_read_b128 v[198:201], v168 offset:34816
	ds_read_b128 v[202:205], v168 offset:35840
	ds_read_b128 v[206:209], v168 offset:36864
	ds_read_b128 v[210:213], v168 offset:37888
	ds_read_b128 v[214:217], v168 offset:38912
	ds_read_b128 v[218:221], v168 offset:39936
	s_mov_b32 m0, s36
	s_nop 0
	global_load_lds_dwordx4 v[224:225], off
	s_mov_b32 m0, s37
	s_nop 0
	global_load_lds_dwordx4 v[226:227], off
	s_mov_b32 m0, s38
	s_nop 0
	global_load_lds_dwordx4 v[228:229], off
	v_lshl_add_u64 v[228:229], s[30:31], 0, v[132:133]
	s_mov_b32 m0, s39
	s_nop 0
	global_load_lds_dwordx4 v[228:229], off
	s_waitcnt vmcnt(8)
	s_waitcnt lgkmcnt(0)
	s_setprio 1
	s_barrier
	v_mfma_f32_16x16x32_bf16 v[126:129], v[148:151], v[190:193], v[126:129]
	v_mfma_f32_16x16x32_bf16 v[122:125], v[156:159], v[190:193], v[122:125]
	v_mfma_f32_16x16x32_bf16 v[110:113], v[148:151], v[198:201], v[110:113]
	v_mfma_f32_16x16x32_bf16 v[106:109], v[156:159], v[198:201], v[106:109]
	v_mfma_f32_16x16x32_bf16 v[94:97], v[148:151], v[206:209], v[94:97]
	v_mfma_f32_16x16x32_bf16 v[90:93], v[156:159], v[206:209], v[90:93]
	v_mfma_f32_16x16x32_bf16 v[86:89], v[148:151], v[214:217], v[86:89]
	v_mfma_f32_16x16x32_bf16 v[78:81], v[156:159], v[214:217], v[78:81]
	v_mfma_f32_16x16x32_bf16 v[126:129], v[152:155], v[194:197], v[126:129]
	v_mfma_f32_16x16x32_bf16 v[122:125], v[170:173], v[194:197], v[122:125]
	v_mfma_f32_16x16x32_bf16 v[110:113], v[152:155], v[202:205], v[110:113]
	v_mfma_f32_16x16x32_bf16 v[106:109], v[170:173], v[202:205], v[106:109]
	v_mfma_f32_16x16x32_bf16 v[94:97], v[152:155], v[210:213], v[94:97]
	v_mfma_f32_16x16x32_bf16 v[90:93], v[170:173], v[210:213], v[90:93]
	v_mfma_f32_16x16x32_bf16 v[86:89], v[152:155], v[218:221], v[86:89]
	v_mfma_f32_16x16x32_bf16 v[78:81], v[170:173], v[218:221], v[78:81]
	v_mfma_f32_16x16x32_bf16 v[118:121], v[174:177], v[190:193], v[118:121]
	v_mfma_f32_16x16x32_bf16 v[114:117], v[182:185], v[190:193], v[114:117]
	v_mfma_f32_16x16x32_bf16 v[102:105], v[174:177], v[198:201], v[102:105]
	v_mfma_f32_16x16x32_bf16 v[98:101], v[182:185], v[198:201], v[98:101]
	v_mfma_f32_16x16x32_bf16 v[82:85], v[174:177], v[206:209], v[82:85]
	v_mfma_f32_16x16x32_bf16 v[74:77], v[182:185], v[206:209], v[74:77]
	v_mfma_f32_16x16x32_bf16 v[70:73], v[174:177], v[214:217], v[70:73]
	v_mfma_f32_16x16x32_bf16 v[66:69], v[182:185], v[214:217], v[66:69]
	v_mfma_f32_16x16x32_bf16 v[118:121], v[178:181], v[194:197], v[118:121]
	v_mfma_f32_16x16x32_bf16 v[114:117], v[186:189], v[194:197], v[114:117]
	v_mfma_f32_16x16x32_bf16 v[102:105], v[178:181], v[202:205], v[102:105]
	v_mfma_f32_16x16x32_bf16 v[98:101], v[186:189], v[202:205], v[98:101]
	v_mfma_f32_16x16x32_bf16 v[82:85], v[178:181], v[210:213], v[82:85]
	v_mfma_f32_16x16x32_bf16 v[74:77], v[186:189], v[210:213], v[74:77]
	v_mfma_f32_16x16x32_bf16 v[70:73], v[178:181], v[218:221], v[70:73]
	v_mfma_f32_16x16x32_bf16 v[66:69], v[186:189], v[218:221], v[66:69]
	s_setprio 0
	s_barrier
	s_add_i32 s30, s56, s33
	v_lshl_add_u64 v[160:161], v[160:161], 0, s[6:7]
	s_mov_b32 m0, s30
	ds_read_b128 v[190:193], v168 offset:49152
	ds_read_b128 v[194:197], v168 offset:50176
	ds_read_b128 v[198:201], v168 offset:51200
	ds_read_b128 v[202:205], v168 offset:52224
	ds_read_b128 v[206:209], v168 offset:53248
	ds_read_b128 v[210:213], v168 offset:54272
	ds_read_b128 v[214:217], v168 offset:55296
	ds_read_b128 v[218:221], v168 offset:56320
	global_load_lds_dwordx4 v[160:161], off
	s_add_i32 m0, s30, 0x2000
	s_add_u32 s28, s28, 0x100080
	v_lshl_add_u64 v[160:161], v[222:223], 0, s[6:7]
	s_addc_u32 s29, s29, 0
	s_add_i32 s30, s57, s33
	global_load_lds_dwordx4 v[160:161], off
	v_lshl_add_u64 v[160:161], s[28:29], 0, v[134:135]
	s_mov_b32 m0, s30
	s_nop 0
	global_load_lds_dwordx4 v[160:161], off
	v_lshl_add_u64 v[160:161], s[28:29], 0, v[130:131]
	s_add_i32 m0, s30, 0x2000
	s_nop 0
	global_load_lds_dwordx4 v[160:161], off
	v_lshl_add_u64 v[224:225], v[224:225], 0, s[6:7]
	v_lshl_add_u64 v[226:227], v[226:227], 0, s[6:7]
	s_waitcnt vmcnt(6)
	s_waitcnt lgkmcnt(0)
	s_setprio 1
	s_barrier
	v_mfma_f32_16x16x32_bf16 v[62:65], v[148:151], v[190:193], v[62:65]
	v_mfma_f32_16x16x32_bf16 v[58:61], v[156:159], v[190:193], v[58:61]
	v_mfma_f32_16x16x32_bf16 v[46:49], v[148:151], v[198:201], v[46:49]
	v_mfma_f32_16x16x32_bf16 v[42:45], v[156:159], v[198:201], v[42:45]
	v_mfma_f32_16x16x32_bf16 v[30:33], v[148:151], v[206:209], v[30:33]
	v_mfma_f32_16x16x32_bf16 v[26:29], v[156:159], v[206:209], v[26:29]
	v_mfma_f32_16x16x32_bf16 v[14:17], v[148:151], v[214:217], v[14:17]
	v_mfma_f32_16x16x32_bf16 v[10:13], v[156:159], v[214:217], v[10:13]
	v_mfma_f32_16x16x32_bf16 v[62:65], v[152:155], v[194:197], v[62:65]
	v_mfma_f32_16x16x32_bf16 v[58:61], v[170:173], v[194:197], v[58:61]
	v_mfma_f32_16x16x32_bf16 v[46:49], v[152:155], v[202:205], v[46:49]
	v_mfma_f32_16x16x32_bf16 v[42:45], v[170:173], v[202:205], v[42:45]
	v_mfma_f32_16x16x32_bf16 v[30:33], v[152:155], v[210:213], v[30:33]
	v_mfma_f32_16x16x32_bf16 v[26:29], v[170:173], v[210:213], v[26:29]
	v_mfma_f32_16x16x32_bf16 v[14:17], v[152:155], v[218:221], v[14:17]
	v_mfma_f32_16x16x32_bf16 v[10:13], v[170:173], v[218:221], v[10:13]
	v_mfma_f32_16x16x32_bf16 v[54:57], v[174:177], v[190:193], v[54:57]
	v_mfma_f32_16x16x32_bf16 v[50:53], v[182:185], v[190:193], v[50:53]
	v_mfma_f32_16x16x32_bf16 v[38:41], v[174:177], v[198:201], v[38:41]
	v_mfma_f32_16x16x32_bf16 v[34:37], v[182:185], v[198:201], v[34:37]
	v_mfma_f32_16x16x32_bf16 v[22:25], v[174:177], v[206:209], v[22:25]
	v_mfma_f32_16x16x32_bf16 v[18:21], v[182:185], v[206:209], v[18:21]
	v_mfma_f32_16x16x32_bf16 v[6:9], v[174:177], v[214:217], v[6:9]
	v_mfma_f32_16x16x32_bf16 v[2:5], v[182:185], v[214:217], v[2:5]
	v_mfma_f32_16x16x32_bf16 v[54:57], v[178:181], v[194:197], v[54:57]
	v_mfma_f32_16x16x32_bf16 v[50:53], v[186:189], v[194:197], v[50:53]
	v_mfma_f32_16x16x32_bf16 v[38:41], v[178:181], v[202:205], v[38:41]
	v_mfma_f32_16x16x32_bf16 v[34:37], v[186:189], v[202:205], v[34:37]
	v_mfma_f32_16x16x32_bf16 v[22:25], v[178:181], v[210:213], v[22:25]
	v_mfma_f32_16x16x32_bf16 v[18:21], v[186:189], v[210:213], v[18:21]
	v_mfma_f32_16x16x32_bf16 v[6:9], v[178:181], v[218:221], v[6:9]
	v_mfma_f32_16x16x32_bf16 v[2:5], v[186:189], v[218:221], v[2:5]
	s_setprio 0
	s_barrier
	s_add_i32 s55, s55, 2
	s_mov_b32 s32, 1
	s_add_u32 s26, s26, 0x100
	s_addc_u32 s27, s27, 0
	s_add_u32 s53, s53, 0x100
	s_addc_u32 s54, s54, 0
	s_cmp_gt_u32 s55, 61
	s_cbranch_scc0 .LBB0_1260
	s_and_b64 vcc, exec, s[8:9]
	s_cbranch_vccz .LBB0_1263
	s_barrier

.Lrebal_skip_1571:
	s_add_i32 m0, s29, 0xc000
	s_nop 0
	global_load_lds_dwordx4 v[146:147], off
	v_lshl_add_u64 v[146:147], s[30:31], 0, v[140:141]
	s_add_i32 m0, s29, 0xe000
	s_nop 0
	global_load_lds_dwordx4 v[146:147], off
	s_waitcnt vmcnt(8)
	s_waitcnt lgkmcnt(0)
	s_setprio 1
	s_barrier
	v_mfma_f32_16x16x32_bf16 v[126:129], v[154:157], v[188:191], v[126:129]
	v_mfma_f32_16x16x32_bf16 v[122:125], v[164:167], v[188:191], v[122:125]
	v_mfma_f32_16x16x32_bf16 v[118:121], v[154:157], v[196:199], v[118:121]
	v_mfma_f32_16x16x32_bf16 v[110:113], v[164:167], v[196:199], v[110:113]
	v_mfma_f32_16x16x32_bf16 v[102:105], v[154:157], v[204:207], v[102:105]
	v_mfma_f32_16x16x32_bf16 v[94:97], v[164:167], v[204:207], v[94:97]
	v_mfma_f32_16x16x32_bf16 v[82:85], v[154:157], v[212:215], v[82:85]
	v_mfma_f32_16x16x32_bf16 v[74:77], v[164:167], v[212:215], v[74:77]
	v_mfma_f32_16x16x32_bf16 v[126:129], v[158:161], v[192:195], v[126:129]
	v_mfma_f32_16x16x32_bf16 v[122:125], v[168:171], v[192:195], v[122:125]
	v_mfma_f32_16x16x32_bf16 v[118:121], v[158:161], v[200:203], v[118:121]
	v_mfma_f32_16x16x32_bf16 v[110:113], v[168:171], v[200:203], v[110:113]
	v_mfma_f32_16x16x32_bf16 v[102:105], v[158:161], v[208:211], v[102:105]
	v_mfma_f32_16x16x32_bf16 v[94:97], v[168:171], v[208:211], v[94:97]
	v_mfma_f32_16x16x32_bf16 v[82:85], v[158:161], v[216:219], v[82:85]
	v_mfma_f32_16x16x32_bf16 v[74:77], v[168:171], v[216:219], v[74:77]
	v_mfma_f32_16x16x32_bf16 v[114:117], v[172:175], v[188:191], v[114:117]
	v_mfma_f32_16x16x32_bf16 v[106:109], v[180:183], v[188:191], v[106:109]
	v_mfma_f32_16x16x32_bf16 v[98:101], v[172:175], v[196:199], v[98:101]
	v_mfma_f32_16x16x32_bf16 v[90:93], v[180:183], v[196:199], v[90:93]
	v_mfma_f32_16x16x32_bf16 v[86:89], v[172:175], v[204:207], v[86:89]
	v_mfma_f32_16x16x32_bf16 v[78:81], v[180:183], v[204:207], v[78:81]
	v_mfma_f32_16x16x32_bf16 v[70:73], v[172:175], v[212:215], v[70:73]
	v_mfma_f32_16x16x32_bf16 v[66:69], v[180:183], v[212:215], v[66:69]
	v_mfma_f32_16x16x32_bf16 v[114:117], v[176:179], v[192:195], v[114:117]
	v_mfma_f32_16x16x32_bf16 v[106:109], v[184:187], v[192:195], v[106:109]
	v_mfma_f32_16x16x32_bf16 v[98:101], v[176:179], v[200:203], v[98:101]
	v_mfma_f32_16x16x32_bf16 v[90:93], v[184:187], v[200:203], v[90:93]
	v_mfma_f32_16x16x32_bf16 v[86:89], v[176:179], v[208:211], v[86:89]
	v_mfma_f32_16x16x32_bf16 v[78:81], v[184:187], v[208:211], v[78:81]
	v_mfma_f32_16x16x32_bf16 v[70:73], v[176:179], v[216:219], v[70:73]
	v_mfma_f32_16x16x32_bf16 v[66:69], v[184:187], v[216:219], v[66:69]
	s_setprio 0
	s_barrier
	s_add_i32 s58, s46, s38
	v_lshl_add_u64 v[146:147], s[34:35], 0, v[132:133]
	s_mov_b32 m0, s58
	ds_read_b128 v[188:191], v152 offset:16384
	ds_read_b128 v[192:195], v152 offset:17408
	ds_read_b128 v[196:199], v152 offset:18432
	ds_read_b128 v[200:203], v152 offset:19456
	ds_read_b128 v[204:207], v152 offset:20480
	ds_read_b128 v[208:211], v152 offset:21504
	ds_read_b128 v[212:215], v152 offset:22528
	ds_read_b128 v[216:219], v152 offset:23552
	global_load_lds_dwordx4 v[146:147], off
	s_add_i32 m0, s58, 0x2000
	s_add_u32 s58, s34, 0x100000
	v_lshl_add_u64 v[220:221], s[34:35], 0, v[136:137]
	s_addc_u32 s59, s35, 0
	s_add_i32 s60, s47, s38
	global_load_lds_dwordx4 v[220:221], off
	v_lshl_add_u64 v[222:223], s[58:59], 0, v[132:133]
	s_mov_b32 m0, s60
	v_lshl_add_u64 v[224:225], s[36:37], 0, v[134:135]
	global_load_lds_dwordx4 v[222:223], off
	v_lshl_add_u64 v[222:223], s[58:59], 0, v[136:137]
	s_add_i32 m0, s60, 0x2000
	s_nop 0
	global_load_lds_dwordx4 v[222:223], off
	v_lshl_add_u64 v[222:223], s[36:37], 0, v[130:131]
	s_waitcnt vmcnt(6)
	s_waitcnt lgkmcnt(0)
	s_setprio 1
	s_barrier
	v_mfma_f32_16x16x32_bf16 v[62:65], v[154:157], v[188:191], v[62:65]
	v_mfma_f32_16x16x32_bf16 v[58:61], v[164:167], v[188:191], v[58:61]
	v_mfma_f32_16x16x32_bf16 v[54:57], v[154:157], v[196:199], v[54:57]
	v_mfma_f32_16x16x32_bf16 v[46:49], v[164:167], v[196:199], v[46:49]
	v_mfma_f32_16x16x32_bf16 v[38:41], v[154:157], v[204:207], v[38:41]
	v_mfma_f32_16x16x32_bf16 v[30:33], v[164:167], v[204:207], v[30:33]
	v_mfma_f32_16x16x32_bf16 v[22:25], v[154:157], v[212:215], v[22:25]
	v_mfma_f32_16x16x32_bf16 v[14:17], v[164:167], v[212:215], v[14:17]
	v_mfma_f32_16x16x32_bf16 v[62:65], v[158:161], v[192:195], v[62:65]
	v_mfma_f32_16x16x32_bf16 v[58:61], v[168:171], v[192:195], v[58:61]
	v_mfma_f32_16x16x32_bf16 v[54:57], v[158:161], v[200:203], v[54:57]
	v_mfma_f32_16x16x32_bf16 v[46:49], v[168:171], v[200:203], v[46:49]
	v_mfma_f32_16x16x32_bf16 v[38:41], v[158:161], v[208:211], v[38:41]
	v_mfma_f32_16x16x32_bf16 v[30:33], v[168:171], v[208:211], v[30:33]
	v_mfma_f32_16x16x32_bf16 v[22:25], v[158:161], v[216:219], v[22:25]
	v_mfma_f32_16x16x32_bf16 v[14:17], v[168:171], v[216:219], v[14:17]
	v_mfma_f32_16x16x32_bf16 v[50:53], v[172:175], v[188:191], v[50:53]
	v_mfma_f32_16x16x32_bf16 v[42:45], v[180:183], v[188:191], v[42:45]
	v_mfma_f32_16x16x32_bf16 v[34:37], v[172:175], v[196:199], v[34:37]
	v_mfma_f32_16x16x32_bf16 v[26:29], v[180:183], v[196:199], v[26:29]
	v_mfma_f32_16x16x32_bf16 v[18:21], v[172:175], v[204:207], v[18:21]
	v_mfma_f32_16x16x32_bf16 v[10:13], v[180:183], v[204:207], v[10:13]
	v_mfma_f32_16x16x32_bf16 v[6:9], v[172:175], v[212:215], v[6:9]
	v_mfma_f32_16x16x32_bf16 v[2:5], v[180:183], v[212:215], v[2:5]
	v_mfma_f32_16x16x32_bf16 v[50:53], v[176:179], v[192:195], v[50:53]
	v_mfma_f32_16x16x32_bf16 v[42:45], v[184:187], v[192:195], v[42:45]
	v_mfma_f32_16x16x32_bf16 v[34:37], v[176:179], v[200:203], v[34:37]
	v_mfma_f32_16x16x32_bf16 v[26:29], v[184:187], v[200:203], v[26:29]
	v_mfma_f32_16x16x32_bf16 v[18:21], v[176:179], v[208:211], v[18:21]
	v_mfma_f32_16x16x32_bf16 v[10:13], v[184:187], v[208:211], v[10:13]
	v_mfma_f32_16x16x32_bf16 v[6:9], v[176:179], v[216:219], v[6:9]
	v_mfma_f32_16x16x32_bf16 v[2:5], v[184:187], v[216:219], v[2:5]
	s_setprio 0
	s_barrier
	s_add_i32 s58, 0, 0x18000
	v_add_u32_e32 v153, s58, v148
	s_add_i32 s59, 0, 0x1c000
	ds_read_b128 v[154:157], v153
	ds_read_b128 v[158:161], v153 offset:1024
	ds_read_b128 v[164:167], v153 offset:2048
	ds_read_b128 v[168:171], v153 offset:3072
	v_add_u32_e32 v153, s59, v148
	ds_read_b128 v[172:175], v153
	ds_read_b128 v[176:179], v153 offset:1024
	ds_read_b128 v[180:183], v153 offset:2048
	ds_read_b128 v[184:187], v153 offset:3072
	s_add_u32 s36, s36, 0x100000
	s_addc_u32 s37, s37, 0
	s_mov_b32 m0, s40
	v_lshl_add_u64 v[226:227], s[36:37], 0, v[130:131]
	ds_read_b128 v[188:191], v152 offset:32768
	ds_read_b128 v[192:195], v152 offset:33792
	ds_read_b128 v[196:199], v152 offset:34816
	ds_read_b128 v[200:203], v152 offset:35840
	ds_read_b128 v[204:207], v152 offset:36864
	ds_read_b128 v[208:211], v152 offset:37888
	ds_read_b128 v[212:215], v152 offset:38912
	ds_read_b128 v[216:219], v152 offset:39936
	s_mov_b32 m0, s29
	s_nop 0
	global_load_lds_dwordx4 v[222:223], off
	s_mov_b32 m0, s39
	s_nop 0
	global_load_lds_dwordx4 v[224:225], off
	s_mov_b32 m0, s40
	s_nop 0
	global_load_lds_dwordx4 v[226:227], off
	v_lshl_add_u64 v[226:227], s[36:37], 0, v[134:135]
	s_mov_b32 m0, s41
	s_nop 0
	global_load_lds_dwordx4 v[226:227], off
	s_waitcnt vmcnt(8)
	s_waitcnt lgkmcnt(0)
	s_setprio 1
	s_barrier
	v_mfma_f32_16x16x32_bf16 v[126:129], v[154:157], v[188:191], v[126:129]
	v_mfma_f32_16x16x32_bf16 v[122:125], v[164:167], v[188:191], v[122:125]
	v_mfma_f32_16x16x32_bf16 v[118:121], v[154:157], v[196:199], v[118:121]
	v_mfma_f32_16x16x32_bf16 v[110:113], v[164:167], v[196:199], v[110:113]
	v_mfma_f32_16x16x32_bf16 v[102:105], v[154:157], v[204:207], v[102:105]
	v_mfma_f32_16x16x32_bf16 v[94:97], v[164:167], v[204:207], v[94:97]
	v_mfma_f32_16x16x32_bf16 v[82:85], v[154:157], v[212:215], v[82:85]
	v_mfma_f32_16x16x32_bf16 v[74:77], v[164:167], v[212:215], v[74:77]
	v_mfma_f32_16x16x32_bf16 v[126:129], v[158:161], v[192:195], v[126:129]
	v_mfma_f32_16x16x32_bf16 v[122:125], v[168:171], v[192:195], v[122:125]
	v_mfma_f32_16x16x32_bf16 v[118:121], v[158:161], v[200:203], v[118:121]
	v_mfma_f32_16x16x32_bf16 v[110:113], v[168:171], v[200:203], v[110:113]
	v_mfma_f32_16x16x32_bf16 v[102:105], v[158:161], v[208:211], v[102:105]
	v_mfma_f32_16x16x32_bf16 v[94:97], v[168:171], v[208:211], v[94:97]
	v_mfma_f32_16x16x32_bf16 v[82:85], v[158:161], v[216:219], v[82:85]
	v_mfma_f32_16x16x32_bf16 v[74:77], v[168:171], v[216:219], v[74:77]
	v_mfma_f32_16x16x32_bf16 v[114:117], v[172:175], v[188:191], v[114:117]
	v_mfma_f32_16x16x32_bf16 v[106:109], v[180:183], v[188:191], v[106:109]
	v_mfma_f32_16x16x32_bf16 v[98:101], v[172:175], v[196:199], v[98:101]
	v_mfma_f32_16x16x32_bf16 v[90:93], v[180:183], v[196:199], v[90:93]
	v_mfma_f32_16x16x32_bf16 v[86:89], v[172:175], v[204:207], v[86:89]
	v_mfma_f32_16x16x32_bf16 v[78:81], v[180:183], v[204:207], v[78:81]
	v_mfma_f32_16x16x32_bf16 v[70:73], v[172:175], v[212:215], v[70:73]
	v_mfma_f32_16x16x32_bf16 v[66:69], v[180:183], v[212:215], v[66:69]
	v_mfma_f32_16x16x32_bf16 v[114:117], v[176:179], v[192:195], v[114:117]
	v_mfma_f32_16x16x32_bf16 v[106:109], v[184:187], v[192:195], v[106:109]
	v_mfma_f32_16x16x32_bf16 v[98:101], v[176:179], v[200:203], v[98:101]
	v_mfma_f32_16x16x32_bf16 v[90:93], v[184:187], v[200:203], v[90:93]
	v_mfma_f32_16x16x32_bf16 v[86:89], v[176:179], v[208:211], v[86:89]
	v_mfma_f32_16x16x32_bf16 v[78:81], v[184:187], v[208:211], v[78:81]
	v_mfma_f32_16x16x32_bf16 v[70:73], v[176:179], v[216:219], v[70:73]
	v_mfma_f32_16x16x32_bf16 v[66:69], v[184:187], v[216:219], v[66:69]
	s_setprio 0
	s_barrier
	s_add_i32 s36, s58, s38
	v_lshl_add_u64 v[146:147], v[146:147], 0, s[10:11]
	s_mov_b32 m0, s36
	ds_read_b128 v[188:191], v152 offset:49152
	ds_read_b128 v[192:195], v152 offset:50176
	ds_read_b128 v[196:199], v152 offset:51200
	ds_read_b128 v[200:203], v152 offset:52224
	ds_read_b128 v[204:207], v152 offset:53248
	ds_read_b128 v[208:211], v152 offset:54272
	ds_read_b128 v[212:215], v152 offset:55296
	ds_read_b128 v[216:219], v152 offset:56320
	global_load_lds_dwordx4 v[146:147], off
	s_add_i32 m0, s36, 0x2000
	s_add_u32 s34, s34, 0x100080
	v_lshl_add_u64 v[146:147], v[220:221], 0, s[10:11]
	s_addc_u32 s35, s35, 0
	s_add_i32 s36, s59, s38
	global_load_lds_dwordx4 v[146:147], off
	v_lshl_add_u64 v[146:147], s[34:35], 0, v[132:133]
	s_mov_b32 m0, s36
	s_nop 0
	global_load_lds_dwordx4 v[146:147], off
	v_lshl_add_u64 v[146:147], s[34:35], 0, v[136:137]
	s_add_i32 m0, s36, 0x2000
	s_nop 0
	global_load_lds_dwordx4 v[146:147], off
	v_lshl_add_u64 v[222:223], v[222:223], 0, s[10:11]
	v_lshl_add_u64 v[224:225], v[224:225], 0, s[10:11]
	s_waitcnt vmcnt(6)
	s_waitcnt lgkmcnt(0)
	s_setprio 1
	s_barrier
	v_mfma_f32_16x16x32_bf16 v[62:65], v[154:157], v[188:191], v[62:65]
	v_mfma_f32_16x16x32_bf16 v[58:61], v[164:167], v[188:191], v[58:61]
	v_mfma_f32_16x16x32_bf16 v[54:57], v[154:157], v[196:199], v[54:57]
	v_mfma_f32_16x16x32_bf16 v[46:49], v[164:167], v[196:199], v[46:49]
	v_mfma_f32_16x16x32_bf16 v[38:41], v[154:157], v[204:207], v[38:41]
	v_mfma_f32_16x16x32_bf16 v[30:33], v[164:167], v[204:207], v[30:33]
	v_mfma_f32_16x16x32_bf16 v[22:25], v[154:157], v[212:215], v[22:25]
	v_mfma_f32_16x16x32_bf16 v[14:17], v[164:167], v[212:215], v[14:17]
	v_mfma_f32_16x16x32_bf16 v[62:65], v[158:161], v[192:195], v[62:65]
	v_mfma_f32_16x16x32_bf16 v[58:61], v[168:171], v[192:195], v[58:61]
	v_mfma_f32_16x16x32_bf16 v[54:57], v[158:161], v[200:203], v[54:57]
	v_mfma_f32_16x16x32_bf16 v[46:49], v[168:171], v[200:203], v[46:49]
	v_mfma_f32_16x16x32_bf16 v[38:41], v[158:161], v[208:211], v[38:41]
	v_mfma_f32_16x16x32_bf16 v[30:33], v[168:171], v[208:211], v[30:33]
	v_mfma_f32_16x16x32_bf16 v[22:25], v[158:161], v[216:219], v[22:25]
	v_mfma_f32_16x16x32_bf16 v[14:17], v[168:171], v[216:219], v[14:17]
	v_mfma_f32_16x16x32_bf16 v[50:53], v[172:175], v[188:191], v[50:53]
	v_mfma_f32_16x16x32_bf16 v[42:45], v[180:183], v[188:191], v[42:45]
	v_mfma_f32_16x16x32_bf16 v[34:37], v[172:175], v[196:199], v[34:37]
	v_mfma_f32_16x16x32_bf16 v[26:29], v[180:183], v[196:199], v[26:29]
	v_mfma_f32_16x16x32_bf16 v[18:21], v[172:175], v[204:207], v[18:21]
	v_mfma_f32_16x16x32_bf16 v[10:13], v[180:183], v[204:207], v[10:13]
	v_mfma_f32_16x16x32_bf16 v[6:9], v[172:175], v[212:215], v[6:9]
	v_mfma_f32_16x16x32_bf16 v[2:5], v[180:183], v[212:215], v[2:5]
	v_mfma_f32_16x16x32_bf16 v[50:53], v[176:179], v[192:195], v[50:53]
	v_mfma_f32_16x16x32_bf16 v[42:45], v[184:187], v[192:195], v[42:45]
	v_mfma_f32_16x16x32_bf16 v[34:37], v[176:179], v[200:203], v[34:37]
	v_mfma_f32_16x16x32_bf16 v[26:29], v[184:187], v[200:203], v[26:29]
	v_mfma_f32_16x16x32_bf16 v[18:21], v[176:179], v[208:211], v[18:21]
	v_mfma_f32_16x16x32_bf16 v[10:13], v[184:187], v[208:211], v[10:13]
	v_mfma_f32_16x16x32_bf16 v[6:9], v[176:179], v[216:219], v[6:9]
	v_mfma_f32_16x16x32_bf16 v[2:5], v[184:187], v[216:219], v[2:5]
	s_setprio 0
	s_barrier
	s_add_i32 s57, s57, 2
	s_mov_b32 s32, 1
	s_add_u32 s30, s30, 0x100
	s_addc_u32 s31, s31, 0
	s_add_u32 s55, s55, 0x100
	s_addc_u32 s56, s56, 0
	s_cmp_gt_u32 s57, 61
	s_cbranch_scc0 .LBB0_1571
	s_and_b64 vcc, exec, s[12:13]
	s_cbranch_vccz .LBB0_1574
	s_barrier

.Lrebal_skip_1695:
	s_add_i32 m0, s23, 0xc000
	s_nop 0
	global_load_lds_dwordx4 v[220:221], off
	v_lshl_add_u64 v[220:221], s[24:25], 0, v[140:141]
	s_add_i32 m0, s23, 0xe000
	s_nop 0
	global_load_lds_dwordx4 v[220:221], off
	s_waitcnt vmcnt(8)
	s_waitcnt lgkmcnt(0)
	s_setprio 1
	s_barrier
	v_mfma_f32_16x16x32_bf16 v[126:129], v[146:149], v[188:191], v[126:129]
	v_mfma_f32_16x16x32_bf16 v[122:125], v[164:167], v[188:191], v[122:125]
	v_mfma_f32_16x16x32_bf16 v[110:113], v[146:149], v[196:199], v[110:113]
	v_mfma_f32_16x16x32_bf16 v[106:109], v[164:167], v[196:199], v[106:109]
	v_mfma_f32_16x16x32_bf16 v[94:97], v[146:149], v[204:207], v[94:97]
	v_mfma_f32_16x16x32_bf16 v[90:93], v[164:167], v[204:207], v[90:93]
	v_mfma_f32_16x16x32_bf16 v[78:81], v[146:149], v[212:215], v[78:81]
	v_mfma_f32_16x16x32_bf16 v[74:77], v[164:167], v[212:215], v[74:77]
	v_mfma_f32_16x16x32_bf16 v[126:129], v[158:161], v[192:195], v[126:129]
	v_mfma_f32_16x16x32_bf16 v[122:125], v[168:171], v[192:195], v[122:125]
	v_mfma_f32_16x16x32_bf16 v[110:113], v[158:161], v[200:203], v[110:113]
	v_mfma_f32_16x16x32_bf16 v[106:109], v[168:171], v[200:203], v[106:109]
	v_mfma_f32_16x16x32_bf16 v[94:97], v[158:161], v[208:211], v[94:97]
	v_mfma_f32_16x16x32_bf16 v[90:93], v[168:171], v[208:211], v[90:93]
	v_mfma_f32_16x16x32_bf16 v[78:81], v[158:161], v[216:219], v[78:81]
	v_mfma_f32_16x16x32_bf16 v[74:77], v[168:171], v[216:219], v[74:77]
	v_mfma_f32_16x16x32_bf16 v[118:121], v[172:175], v[188:191], v[118:121]
	v_mfma_f32_16x16x32_bf16 v[114:117], v[180:183], v[188:191], v[114:117]
	v_mfma_f32_16x16x32_bf16 v[102:105], v[172:175], v[196:199], v[102:105]
	v_mfma_f32_16x16x32_bf16 v[98:101], v[180:183], v[196:199], v[98:101]
	v_mfma_f32_16x16x32_bf16 v[86:89], v[172:175], v[204:207], v[86:89]
	v_mfma_f32_16x16x32_bf16 v[82:85], v[180:183], v[204:207], v[82:85]
	v_mfma_f32_16x16x32_bf16 v[70:73], v[172:175], v[212:215], v[70:73]
	v_mfma_f32_16x16x32_bf16 v[66:69], v[180:183], v[212:215], v[66:69]
	v_mfma_f32_16x16x32_bf16 v[118:121], v[176:179], v[192:195], v[118:121]
	v_mfma_f32_16x16x32_bf16 v[114:117], v[184:187], v[192:195], v[114:117]
	v_mfma_f32_16x16x32_bf16 v[102:105], v[176:179], v[200:203], v[102:105]
	v_mfma_f32_16x16x32_bf16 v[98:101], v[184:187], v[200:203], v[98:101]
	v_mfma_f32_16x16x32_bf16 v[86:89], v[176:179], v[208:211], v[86:89]
	v_mfma_f32_16x16x32_bf16 v[82:85], v[184:187], v[208:211], v[82:85]
	v_mfma_f32_16x16x32_bf16 v[70:73], v[176:179], v[216:219], v[70:73]
	v_mfma_f32_16x16x32_bf16 v[66:69], v[184:187], v[216:219], v[66:69]
	s_setprio 0
	s_barrier
	s_add_i32 s50, s43, s33
	v_lshl_add_u64 v[220:221], s[26:27], 0, v[132:133]
	s_mov_b32 m0, s50
	ds_read_b128 v[188:191], v156 offset:16384
	ds_read_b128 v[192:195], v156 offset:17408
	ds_read_b128 v[196:199], v156 offset:18432
	ds_read_b128 v[200:203], v156 offset:19456
	ds_read_b128 v[204:207], v156 offset:20480
	ds_read_b128 v[208:211], v156 offset:21504
	ds_read_b128 v[212:215], v156 offset:22528
	ds_read_b128 v[216:219], v156 offset:23552
	global_load_lds_dwordx4 v[220:221], off
	s_add_i32 m0, s50, 0x2000
	s_add_u32 s50, s26, 0x100000
	v_lshl_add_u64 v[222:223], s[26:27], 0, v[136:137]
	s_addc_u32 s51, s27, 0
	s_add_i32 s52, s44, s33
	global_load_lds_dwordx4 v[222:223], off
	v_lshl_add_u64 v[224:225], s[50:51], 0, v[132:133]
	s_mov_b32 m0, s52
	v_lshl_add_u64 v[226:227], s[28:29], 0, v[134:135]
	global_load_lds_dwordx4 v[224:225], off
	v_lshl_add_u64 v[224:225], s[50:51], 0, v[136:137]
	s_add_i32 m0, s52, 0x2000
	s_nop 0
	global_load_lds_dwordx4 v[224:225], off
	v_lshl_add_u64 v[224:225], s[28:29], 0, v[130:131]
	s_waitcnt vmcnt(6)
	s_waitcnt lgkmcnt(0)
	s_setprio 1
	s_barrier
	v_mfma_f32_16x16x32_bf16 v[62:65], v[146:149], v[188:191], v[62:65]
	v_mfma_f32_16x16x32_bf16 v[58:61], v[164:167], v[188:191], v[58:61]
	v_mfma_f32_16x16x32_bf16 v[46:49], v[146:149], v[196:199], v[46:49]
	v_mfma_f32_16x16x32_bf16 v[42:45], v[164:167], v[196:199], v[42:45]
	v_mfma_f32_16x16x32_bf16 v[30:33], v[146:149], v[204:207], v[30:33]
	v_mfma_f32_16x16x32_bf16 v[26:29], v[164:167], v[204:207], v[26:29]
	v_mfma_f32_16x16x32_bf16 v[14:17], v[146:149], v[212:215], v[14:17]
	v_mfma_f32_16x16x32_bf16 v[10:13], v[164:167], v[212:215], v[10:13]
	v_mfma_f32_16x16x32_bf16 v[62:65], v[158:161], v[192:195], v[62:65]
	v_mfma_f32_16x16x32_bf16 v[58:61], v[168:171], v[192:195], v[58:61]
	v_mfma_f32_16x16x32_bf16 v[46:49], v[158:161], v[200:203], v[46:49]
	v_mfma_f32_16x16x32_bf16 v[42:45], v[168:171], v[200:203], v[42:45]
	v_mfma_f32_16x16x32_bf16 v[30:33], v[158:161], v[208:211], v[30:33]
	v_mfma_f32_16x16x32_bf16 v[26:29], v[168:171], v[208:211], v[26:29]
	v_mfma_f32_16x16x32_bf16 v[14:17], v[158:161], v[216:219], v[14:17]
	v_mfma_f32_16x16x32_bf16 v[10:13], v[168:171], v[216:219], v[10:13]
	v_mfma_f32_16x16x32_bf16 v[54:57], v[172:175], v[188:191], v[54:57]
	v_mfma_f32_16x16x32_bf16 v[50:53], v[180:183], v[188:191], v[50:53]
	v_mfma_f32_16x16x32_bf16 v[38:41], v[172:175], v[196:199], v[38:41]
	v_mfma_f32_16x16x32_bf16 v[34:37], v[180:183], v[196:199], v[34:37]
	v_mfma_f32_16x16x32_bf16 v[22:25], v[172:175], v[204:207], v[22:25]
	v_mfma_f32_16x16x32_bf16 v[18:21], v[180:183], v[204:207], v[18:21]
	v_mfma_f32_16x16x32_bf16 v[6:9], v[172:175], v[212:215], v[6:9]
	v_mfma_f32_16x16x32_bf16 v[2:5], v[180:183], v[212:215], v[2:5]
	v_mfma_f32_16x16x32_bf16 v[54:57], v[176:179], v[192:195], v[54:57]
	v_mfma_f32_16x16x32_bf16 v[50:53], v[184:187], v[192:195], v[50:53]
	v_mfma_f32_16x16x32_bf16 v[38:41], v[176:179], v[200:203], v[38:41]
	v_mfma_f32_16x16x32_bf16 v[34:37], v[184:187], v[200:203], v[34:37]
	v_mfma_f32_16x16x32_bf16 v[22:25], v[176:179], v[208:211], v[22:25]
	v_mfma_f32_16x16x32_bf16 v[18:21], v[184:187], v[208:211], v[18:21]
	v_mfma_f32_16x16x32_bf16 v[6:9], v[176:179], v[216:219], v[6:9]
	v_mfma_f32_16x16x32_bf16 v[2:5], v[184:187], v[216:219], v[2:5]
	s_setprio 0
	s_barrier
	s_add_i32 s50, 0, 0x18000
	v_add_u32_e32 v150, s50, v151
	s_add_i32 s51, 0, 0x1c000
	ds_read_b128 v[146:149], v150
	ds_read_b128 v[158:161], v150 offset:1024
	ds_read_b128 v[164:167], v150 offset:2048
	ds_read_b128 v[168:171], v150 offset:3072
	v_add_u32_e32 v150, s51, v151
	ds_read_b128 v[172:175], v150
	ds_read_b128 v[176:179], v150 offset:1024
	ds_read_b128 v[180:183], v150 offset:2048
	ds_read_b128 v[184:187], v150 offset:3072
	s_add_u32 s28, s28, 0x100000
	s_addc_u32 s29, s29, 0
	s_mov_b32 m0, s35
	v_lshl_add_u64 v[228:229], s[28:29], 0, v[130:131]
	ds_read_b128 v[188:191], v156 offset:32768
	ds_read_b128 v[192:195], v156 offset:33792
	ds_read_b128 v[196:199], v156 offset:34816
	ds_read_b128 v[200:203], v156 offset:35840
	ds_read_b128 v[204:207], v156 offset:36864
	ds_read_b128 v[208:211], v156 offset:37888
	ds_read_b128 v[212:215], v156 offset:38912
	ds_read_b128 v[216:219], v156 offset:39936
	s_mov_b32 m0, s23
	s_nop 0
	global_load_lds_dwordx4 v[224:225], off
	s_mov_b32 m0, s34
	s_nop 0
	global_load_lds_dwordx4 v[226:227], off
	s_mov_b32 m0, s35
	s_nop 0
	global_load_lds_dwordx4 v[228:229], off
	v_lshl_add_u64 v[228:229], s[28:29], 0, v[134:135]
	s_mov_b32 m0, s36
	s_nop 0
	global_load_lds_dwordx4 v[228:229], off
	s_waitcnt vmcnt(8)
	s_waitcnt lgkmcnt(0)
	s_setprio 1
	s_barrier
	v_mfma_f32_16x16x32_bf16 v[126:129], v[146:149], v[188:191], v[126:129]
	v_mfma_f32_16x16x32_bf16 v[122:125], v[164:167], v[188:191], v[122:125]
	v_mfma_f32_16x16x32_bf16 v[110:113], v[146:149], v[196:199], v[110:113]
	v_mfma_f32_16x16x32_bf16 v[106:109], v[164:167], v[196:199], v[106:109]
	v_mfma_f32_16x16x32_bf16 v[94:97], v[146:149], v[204:207], v[94:97]
	v_mfma_f32_16x16x32_bf16 v[90:93], v[164:167], v[204:207], v[90:93]
	v_mfma_f32_16x16x32_bf16 v[78:81], v[146:149], v[212:215], v[78:81]
	v_mfma_f32_16x16x32_bf16 v[74:77], v[164:167], v[212:215], v[74:77]
	v_mfma_f32_16x16x32_bf16 v[126:129], v[158:161], v[192:195], v[126:129]
	v_mfma_f32_16x16x32_bf16 v[122:125], v[168:171], v[192:195], v[122:125]
	v_mfma_f32_16x16x32_bf16 v[110:113], v[158:161], v[200:203], v[110:113]
	v_mfma_f32_16x16x32_bf16 v[106:109], v[168:171], v[200:203], v[106:109]
	v_mfma_f32_16x16x32_bf16 v[94:97], v[158:161], v[208:211], v[94:97]
	v_mfma_f32_16x16x32_bf16 v[90:93], v[168:171], v[208:211], v[90:93]
	v_mfma_f32_16x16x32_bf16 v[78:81], v[158:161], v[216:219], v[78:81]
	v_mfma_f32_16x16x32_bf16 v[74:77], v[168:171], v[216:219], v[74:77]
	v_mfma_f32_16x16x32_bf16 v[118:121], v[172:175], v[188:191], v[118:121]
	v_mfma_f32_16x16x32_bf16 v[114:117], v[180:183], v[188:191], v[114:117]
	v_mfma_f32_16x16x32_bf16 v[102:105], v[172:175], v[196:199], v[102:105]
	v_mfma_f32_16x16x32_bf16 v[98:101], v[180:183], v[196:199], v[98:101]
	v_mfma_f32_16x16x32_bf16 v[86:89], v[172:175], v[204:207], v[86:89]
	v_mfma_f32_16x16x32_bf16 v[82:85], v[180:183], v[204:207], v[82:85]
	v_mfma_f32_16x16x32_bf16 v[70:73], v[172:175], v[212:215], v[70:73]
	v_mfma_f32_16x16x32_bf16 v[66:69], v[180:183], v[212:215], v[66:69]
	v_mfma_f32_16x16x32_bf16 v[118:121], v[176:179], v[192:195], v[118:121]
	v_mfma_f32_16x16x32_bf16 v[114:117], v[184:187], v[192:195], v[114:117]
	v_mfma_f32_16x16x32_bf16 v[102:105], v[176:179], v[200:203], v[102:105]
	v_mfma_f32_16x16x32_bf16 v[98:101], v[184:187], v[200:203], v[98:101]
	v_mfma_f32_16x16x32_bf16 v[86:89], v[176:179], v[208:211], v[86:89]
	v_mfma_f32_16x16x32_bf16 v[82:85], v[184:187], v[208:211], v[82:85]
	v_mfma_f32_16x16x32_bf16 v[70:73], v[176:179], v[216:219], v[70:73]
	v_mfma_f32_16x16x32_bf16 v[66:69], v[184:187], v[216:219], v[66:69]
	s_setprio 0
	s_barrier
	s_add_i32 s28, s50, s33
	v_lshl_add_u64 v[220:221], v[220:221], 0, s[8:9]
	s_mov_b32 m0, s28
	ds_read_b128 v[188:191], v156 offset:49152
	ds_read_b128 v[192:195], v156 offset:50176
	ds_read_b128 v[196:199], v156 offset:51200
	ds_read_b128 v[200:203], v156 offset:52224
	ds_read_b128 v[204:207], v156 offset:53248
	ds_read_b128 v[208:211], v156 offset:54272
	ds_read_b128 v[212:215], v156 offset:55296
	ds_read_b128 v[216:219], v156 offset:56320
	global_load_lds_dwordx4 v[220:221], off
	s_add_i32 m0, s28, 0x2000
	s_add_u32 s26, s26, 0x100080
	v_lshl_add_u64 v[220:221], v[222:223], 0, s[8:9]
	s_addc_u32 s27, s27, 0
	s_add_i32 s28, s51, s33
	global_load_lds_dwordx4 v[220:221], off
	v_lshl_add_u64 v[220:221], s[26:27], 0, v[132:133]
	s_mov_b32 m0, s28
	s_nop 0
	global_load_lds_dwordx4 v[220:221], off
	v_lshl_add_u64 v[220:221], s[26:27], 0, v[136:137]
	s_add_i32 m0, s28, 0x2000
	s_nop 0
	global_load_lds_dwordx4 v[220:221], off
	v_lshl_add_u64 v[224:225], v[224:225], 0, s[8:9]
	v_lshl_add_u64 v[226:227], v[226:227], 0, s[8:9]
	s_waitcnt vmcnt(6)
	s_waitcnt lgkmcnt(0)
	s_setprio 1
	s_barrier
	v_mfma_f32_16x16x32_bf16 v[62:65], v[146:149], v[188:191], v[62:65]
	v_mfma_f32_16x16x32_bf16 v[58:61], v[164:167], v[188:191], v[58:61]
	v_mfma_f32_16x16x32_bf16 v[46:49], v[146:149], v[196:199], v[46:49]
	v_mfma_f32_16x16x32_bf16 v[42:45], v[164:167], v[196:199], v[42:45]
	v_mfma_f32_16x16x32_bf16 v[30:33], v[146:149], v[204:207], v[30:33]
	v_mfma_f32_16x16x32_bf16 v[26:29], v[164:167], v[204:207], v[26:29]
	v_mfma_f32_16x16x32_bf16 v[14:17], v[146:149], v[212:215], v[14:17]
	v_mfma_f32_16x16x32_bf16 v[10:13], v[164:167], v[212:215], v[10:13]
	v_mfma_f32_16x16x32_bf16 v[62:65], v[158:161], v[192:195], v[62:65]
	v_mfma_f32_16x16x32_bf16 v[58:61], v[168:171], v[192:195], v[58:61]
	v_mfma_f32_16x16x32_bf16 v[46:49], v[158:161], v[200:203], v[46:49]
	v_mfma_f32_16x16x32_bf16 v[42:45], v[168:171], v[200:203], v[42:45]
	v_mfma_f32_16x16x32_bf16 v[30:33], v[158:161], v[208:211], v[30:33]
	v_mfma_f32_16x16x32_bf16 v[26:29], v[168:171], v[208:211], v[26:29]
	v_mfma_f32_16x16x32_bf16 v[14:17], v[158:161], v[216:219], v[14:17]
	v_mfma_f32_16x16x32_bf16 v[10:13], v[168:171], v[216:219], v[10:13]
	v_mfma_f32_16x16x32_bf16 v[54:57], v[172:175], v[188:191], v[54:57]
	v_mfma_f32_16x16x32_bf16 v[50:53], v[180:183], v[188:191], v[50:53]
	v_mfma_f32_16x16x32_bf16 v[38:41], v[172:175], v[196:199], v[38:41]
	v_mfma_f32_16x16x32_bf16 v[34:37], v[180:183], v[196:199], v[34:37]
	v_mfma_f32_16x16x32_bf16 v[22:25], v[172:175], v[204:207], v[22:25]
	v_mfma_f32_16x16x32_bf16 v[18:21], v[180:183], v[204:207], v[18:21]
	v_mfma_f32_16x16x32_bf16 v[6:9], v[172:175], v[212:215], v[6:9]
	v_mfma_f32_16x16x32_bf16 v[2:5], v[180:183], v[212:215], v[2:5]
	v_mfma_f32_16x16x32_bf16 v[54:57], v[176:179], v[192:195], v[54:57]
	v_mfma_f32_16x16x32_bf16 v[50:53], v[184:187], v[192:195], v[50:53]
	v_mfma_f32_16x16x32_bf16 v[38:41], v[176:179], v[200:203], v[38:41]
	v_mfma_f32_16x16x32_bf16 v[34:37], v[184:187], v[200:203], v[34:37]
	v_mfma_f32_16x16x32_bf16 v[22:25], v[176:179], v[208:211], v[22:25]
	v_mfma_f32_16x16x32_bf16 v[18:21], v[184:187], v[208:211], v[18:21]
	v_mfma_f32_16x16x32_bf16 v[6:9], v[176:179], v[216:219], v[6:9]
	v_mfma_f32_16x16x32_bf16 v[2:5], v[184:187], v[216:219], v[2:5]
	s_setprio 0
	s_barrier
	s_add_i32 s49, s49, 2
	s_mov_b32 s32, 1
	s_add_u32 s24, s24, 0x100
	s_addc_u32 s25, s25, 0
	s_add_u32 s47, s47, 0x100
	s_addc_u32 s48, s48, 0
	s_cmp_gt_u32 s49, 61
	s_cbranch_scc0 .LBB0_1695
	s_and_b64 vcc, exec, s[10:11]
	s_cbranch_vccz .LBB0_1698
	s_barrier

.Lrebal_skip_1853:
	s_add_i32 m0, s33, 0xc000
	s_nop 0
	global_load_lds_dwordx4 v[146:147], off
	v_lshl_add_u64 v[146:147], s[22:23], 0, v[140:141]
	s_add_i32 m0, s33, 0xe000
	s_nop 0
	global_load_lds_dwordx4 v[146:147], off
	s_waitcnt vmcnt(8)
	s_waitcnt lgkmcnt(0)
	s_setprio 1
	s_barrier
	v_mfma_f32_16x16x32_bf16 v[126:129], v[154:157], v[188:191], v[126:129]
	v_mfma_f32_16x16x32_bf16 v[122:125], v[164:167], v[188:191], v[122:125]
	v_mfma_f32_16x16x32_bf16 v[118:121], v[154:157], v[196:199], v[118:121]
	v_mfma_f32_16x16x32_bf16 v[110:113], v[164:167], v[196:199], v[110:113]
	v_mfma_f32_16x16x32_bf16 v[102:105], v[154:157], v[204:207], v[102:105]
	v_mfma_f32_16x16x32_bf16 v[94:97], v[164:167], v[204:207], v[94:97]
	v_mfma_f32_16x16x32_bf16 v[82:85], v[154:157], v[212:215], v[82:85]
	v_mfma_f32_16x16x32_bf16 v[74:77], v[164:167], v[212:215], v[74:77]
	v_mfma_f32_16x16x32_bf16 v[126:129], v[158:161], v[192:195], v[126:129]
	v_mfma_f32_16x16x32_bf16 v[122:125], v[168:171], v[192:195], v[122:125]
	v_mfma_f32_16x16x32_bf16 v[118:121], v[158:161], v[200:203], v[118:121]
	v_mfma_f32_16x16x32_bf16 v[110:113], v[168:171], v[200:203], v[110:113]
	v_mfma_f32_16x16x32_bf16 v[102:105], v[158:161], v[208:211], v[102:105]
	v_mfma_f32_16x16x32_bf16 v[94:97], v[168:171], v[208:211], v[94:97]
	v_mfma_f32_16x16x32_bf16 v[82:85], v[158:161], v[216:219], v[82:85]
	v_mfma_f32_16x16x32_bf16 v[74:77], v[168:171], v[216:219], v[74:77]
	v_mfma_f32_16x16x32_bf16 v[114:117], v[172:175], v[188:191], v[114:117]
	v_mfma_f32_16x16x32_bf16 v[106:109], v[180:183], v[188:191], v[106:109]
	v_mfma_f32_16x16x32_bf16 v[98:101], v[172:175], v[196:199], v[98:101]
	v_mfma_f32_16x16x32_bf16 v[90:93], v[180:183], v[196:199], v[90:93]
	v_mfma_f32_16x16x32_bf16 v[86:89], v[172:175], v[204:207], v[86:89]
	v_mfma_f32_16x16x32_bf16 v[78:81], v[180:183], v[204:207], v[78:81]
	v_mfma_f32_16x16x32_bf16 v[70:73], v[172:175], v[212:215], v[70:73]
	v_mfma_f32_16x16x32_bf16 v[66:69], v[180:183], v[212:215], v[66:69]
	v_mfma_f32_16x16x32_bf16 v[114:117], v[176:179], v[192:195], v[114:117]
	v_mfma_f32_16x16x32_bf16 v[106:109], v[184:187], v[192:195], v[106:109]
	v_mfma_f32_16x16x32_bf16 v[98:101], v[176:179], v[200:203], v[98:101]
	v_mfma_f32_16x16x32_bf16 v[90:93], v[184:187], v[200:203], v[90:93]
	v_mfma_f32_16x16x32_bf16 v[86:89], v[176:179], v[208:211], v[86:89]
	v_mfma_f32_16x16x32_bf16 v[78:81], v[184:187], v[208:211], v[78:81]
	v_mfma_f32_16x16x32_bf16 v[70:73], v[176:179], v[216:219], v[70:73]
	v_mfma_f32_16x16x32_bf16 v[66:69], v[184:187], v[216:219], v[66:69]
	s_setprio 0
	s_barrier
	s_add_i32 s54, s41, s31
	v_lshl_add_u64 v[146:147], s[24:25], 0, v[132:133]
	s_mov_b32 m0, s54
	ds_read_b128 v[188:191], v152 offset:16384
	ds_read_b128 v[192:195], v152 offset:17408
	ds_read_b128 v[196:199], v152 offset:18432
	ds_read_b128 v[200:203], v152 offset:19456
	ds_read_b128 v[204:207], v152 offset:20480
	ds_read_b128 v[208:211], v152 offset:21504
	ds_read_b128 v[212:215], v152 offset:22528
	ds_read_b128 v[216:219], v152 offset:23552
	global_load_lds_dwordx4 v[146:147], off
	s_add_i32 m0, s54, 0x2000
	s_add_u32 s54, s24, 0x2b0000
	v_lshl_add_u64 v[220:221], s[24:25], 0, v[136:137]
	s_addc_u32 s55, s25, 0
	s_add_i32 s56, s42, s31
	global_load_lds_dwordx4 v[220:221], off
	v_lshl_add_u64 v[222:223], s[54:55], 0, v[132:133]
	s_mov_b32 m0, s56
	v_lshl_add_u64 v[224:225], s[26:27], 0, v[134:135]
	global_load_lds_dwordx4 v[222:223], off
	v_lshl_add_u64 v[222:223], s[54:55], 0, v[136:137]
	s_add_i32 m0, s56, 0x2000
	s_nop 0
	global_load_lds_dwordx4 v[222:223], off
	v_lshl_add_u64 v[222:223], s[26:27], 0, v[130:131]
	s_waitcnt vmcnt(6)
	s_waitcnt lgkmcnt(0)
	s_setprio 1
	s_barrier
	v_mfma_f32_16x16x32_bf16 v[62:65], v[154:157], v[188:191], v[62:65]
	v_mfma_f32_16x16x32_bf16 v[58:61], v[164:167], v[188:191], v[58:61]
	v_mfma_f32_16x16x32_bf16 v[54:57], v[154:157], v[196:199], v[54:57]
	v_mfma_f32_16x16x32_bf16 v[46:49], v[164:167], v[196:199], v[46:49]
	v_mfma_f32_16x16x32_bf16 v[38:41], v[154:157], v[204:207], v[38:41]
	v_mfma_f32_16x16x32_bf16 v[30:33], v[164:167], v[204:207], v[30:33]
	v_mfma_f32_16x16x32_bf16 v[22:25], v[154:157], v[212:215], v[22:25]
	v_mfma_f32_16x16x32_bf16 v[14:17], v[164:167], v[212:215], v[14:17]
	v_mfma_f32_16x16x32_bf16 v[62:65], v[158:161], v[192:195], v[62:65]
	v_mfma_f32_16x16x32_bf16 v[58:61], v[168:171], v[192:195], v[58:61]
	v_mfma_f32_16x16x32_bf16 v[54:57], v[158:161], v[200:203], v[54:57]
	v_mfma_f32_16x16x32_bf16 v[46:49], v[168:171], v[200:203], v[46:49]
	v_mfma_f32_16x16x32_bf16 v[38:41], v[158:161], v[208:211], v[38:41]
	v_mfma_f32_16x16x32_bf16 v[30:33], v[168:171], v[208:211], v[30:33]
	v_mfma_f32_16x16x32_bf16 v[22:25], v[158:161], v[216:219], v[22:25]
	v_mfma_f32_16x16x32_bf16 v[14:17], v[168:171], v[216:219], v[14:17]
	v_mfma_f32_16x16x32_bf16 v[50:53], v[172:175], v[188:191], v[50:53]
	v_mfma_f32_16x16x32_bf16 v[42:45], v[180:183], v[188:191], v[42:45]
	v_mfma_f32_16x16x32_bf16 v[34:37], v[172:175], v[196:199], v[34:37]
	v_mfma_f32_16x16x32_bf16 v[26:29], v[180:183], v[196:199], v[26:29]
	v_mfma_f32_16x16x32_bf16 v[18:21], v[172:175], v[204:207], v[18:21]
	v_mfma_f32_16x16x32_bf16 v[10:13], v[180:183], v[204:207], v[10:13]
	v_mfma_f32_16x16x32_bf16 v[6:9], v[172:175], v[212:215], v[6:9]
	v_mfma_f32_16x16x32_bf16 v[2:5], v[180:183], v[212:215], v[2:5]
	v_mfma_f32_16x16x32_bf16 v[50:53], v[176:179], v[192:195], v[50:53]
	v_mfma_f32_16x16x32_bf16 v[42:45], v[184:187], v[192:195], v[42:45]
	v_mfma_f32_16x16x32_bf16 v[34:37], v[176:179], v[200:203], v[34:37]
	v_mfma_f32_16x16x32_bf16 v[26:29], v[184:187], v[200:203], v[26:29]
	v_mfma_f32_16x16x32_bf16 v[18:21], v[176:179], v[208:211], v[18:21]
	v_mfma_f32_16x16x32_bf16 v[10:13], v[184:187], v[208:211], v[10:13]
	v_mfma_f32_16x16x32_bf16 v[6:9], v[176:179], v[216:219], v[6:9]
	v_mfma_f32_16x16x32_bf16 v[2:5], v[184:187], v[216:219], v[2:5]
	s_setprio 0
	s_barrier
	s_add_i32 s54, 0, 0x18000
	v_add_u32_e32 v153, s54, v148
	s_add_i32 s55, 0, 0x1c000
	ds_read_b128 v[154:157], v153
	ds_read_b128 v[158:161], v153 offset:1024
	ds_read_b128 v[164:167], v153 offset:2048
	ds_read_b128 v[168:171], v153 offset:3072
	v_add_u32_e32 v153, s55, v148
	ds_read_b128 v[172:175], v153
	ds_read_b128 v[176:179], v153 offset:1024
	ds_read_b128 v[180:183], v153 offset:2048
	ds_read_b128 v[184:187], v153 offset:3072
	s_add_u32 s26, s26, 0x2b0000
	s_addc_u32 s27, s27, 0
	s_mov_b32 m0, s35
	v_lshl_add_u64 v[226:227], s[26:27], 0, v[130:131]
	ds_read_b128 v[188:191], v152 offset:32768
	ds_read_b128 v[192:195], v152 offset:33792
	ds_read_b128 v[196:199], v152 offset:34816
	ds_read_b128 v[200:203], v152 offset:35840
	ds_read_b128 v[204:207], v152 offset:36864
	ds_read_b128 v[208:211], v152 offset:37888
	ds_read_b128 v[212:215], v152 offset:38912
	ds_read_b128 v[216:219], v152 offset:39936
	s_mov_b32 m0, s33
	s_nop 0
	global_load_lds_dwordx4 v[222:223], off
	s_mov_b32 m0, s34
	s_nop 0
	global_load_lds_dwordx4 v[224:225], off
	s_mov_b32 m0, s35
	s_nop 0
	global_load_lds_dwordx4 v[226:227], off
	v_lshl_add_u64 v[226:227], s[26:27], 0, v[134:135]
	s_mov_b32 m0, s36
	s_nop 0
	global_load_lds_dwordx4 v[226:227], off
	s_waitcnt vmcnt(8)
	s_waitcnt lgkmcnt(0)
	s_setprio 1
	s_barrier
	v_mfma_f32_16x16x32_bf16 v[126:129], v[154:157], v[188:191], v[126:129]
	v_mfma_f32_16x16x32_bf16 v[122:125], v[164:167], v[188:191], v[122:125]
	v_mfma_f32_16x16x32_bf16 v[118:121], v[154:157], v[196:199], v[118:121]
	v_mfma_f32_16x16x32_bf16 v[110:113], v[164:167], v[196:199], v[110:113]
	v_mfma_f32_16x16x32_bf16 v[102:105], v[154:157], v[204:207], v[102:105]
	v_mfma_f32_16x16x32_bf16 v[94:97], v[164:167], v[204:207], v[94:97]
	v_mfma_f32_16x16x32_bf16 v[82:85], v[154:157], v[212:215], v[82:85]
	v_mfma_f32_16x16x32_bf16 v[74:77], v[164:167], v[212:215], v[74:77]
	v_mfma_f32_16x16x32_bf16 v[126:129], v[158:161], v[192:195], v[126:129]
	v_mfma_f32_16x16x32_bf16 v[122:125], v[168:171], v[192:195], v[122:125]
	v_mfma_f32_16x16x32_bf16 v[118:121], v[158:161], v[200:203], v[118:121]
	v_mfma_f32_16x16x32_bf16 v[110:113], v[168:171], v[200:203], v[110:113]
	v_mfma_f32_16x16x32_bf16 v[102:105], v[158:161], v[208:211], v[102:105]
	v_mfma_f32_16x16x32_bf16 v[94:97], v[168:171], v[208:211], v[94:97]
	v_mfma_f32_16x16x32_bf16 v[82:85], v[158:161], v[216:219], v[82:85]
	v_mfma_f32_16x16x32_bf16 v[74:77], v[168:171], v[216:219], v[74:77]
	v_mfma_f32_16x16x32_bf16 v[114:117], v[172:175], v[188:191], v[114:117]
	v_mfma_f32_16x16x32_bf16 v[106:109], v[180:183], v[188:191], v[106:109]
	v_mfma_f32_16x16x32_bf16 v[98:101], v[172:175], v[196:199], v[98:101]
	v_mfma_f32_16x16x32_bf16 v[90:93], v[180:183], v[196:199], v[90:93]
	v_mfma_f32_16x16x32_bf16 v[86:89], v[172:175], v[204:207], v[86:89]
	v_mfma_f32_16x16x32_bf16 v[78:81], v[180:183], v[204:207], v[78:81]
	v_mfma_f32_16x16x32_bf16 v[70:73], v[172:175], v[212:215], v[70:73]
	v_mfma_f32_16x16x32_bf16 v[66:69], v[180:183], v[212:215], v[66:69]
	v_mfma_f32_16x16x32_bf16 v[114:117], v[176:179], v[192:195], v[114:117]
	v_mfma_f32_16x16x32_bf16 v[106:109], v[184:187], v[192:195], v[106:109]
	v_mfma_f32_16x16x32_bf16 v[98:101], v[176:179], v[200:203], v[98:101]
	v_mfma_f32_16x16x32_bf16 v[90:93], v[184:187], v[200:203], v[90:93]
	v_mfma_f32_16x16x32_bf16 v[86:89], v[176:179], v[208:211], v[86:89]
	v_mfma_f32_16x16x32_bf16 v[78:81], v[184:187], v[208:211], v[78:81]
	v_mfma_f32_16x16x32_bf16 v[70:73], v[176:179], v[216:219], v[70:73]
	v_mfma_f32_16x16x32_bf16 v[66:69], v[184:187], v[216:219], v[66:69]
	s_setprio 0
	s_barrier
	s_add_i32 s26, s54, s31
	v_lshl_add_u64 v[146:147], v[146:147], 0, s[8:9]
	s_mov_b32 m0, s26
	ds_read_b128 v[188:191], v152 offset:49152
	ds_read_b128 v[192:195], v152 offset:50176
	ds_read_b128 v[196:199], v152 offset:51200
	ds_read_b128 v[200:203], v152 offset:52224
	ds_read_b128 v[204:207], v152 offset:53248
	ds_read_b128 v[208:211], v152 offset:54272
	ds_read_b128 v[212:215], v152 offset:55296
	ds_read_b128 v[216:219], v152 offset:56320
	global_load_lds_dwordx4 v[146:147], off
	s_add_i32 m0, s26, 0x2000
	s_add_u32 s24, s24, 0x2b0080
	v_lshl_add_u64 v[146:147], v[220:221], 0, s[8:9]
	s_addc_u32 s25, s25, 0
	s_add_i32 s26, s55, s31
	global_load_lds_dwordx4 v[146:147], off
	v_lshl_add_u64 v[146:147], s[24:25], 0, v[132:133]
	s_mov_b32 m0, s26
	s_nop 0
	global_load_lds_dwordx4 v[146:147], off
	v_lshl_add_u64 v[146:147], s[24:25], 0, v[136:137]
	s_add_i32 m0, s26, 0x2000
	s_nop 0
	global_load_lds_dwordx4 v[146:147], off
	v_lshl_add_u64 v[222:223], v[222:223], 0, s[8:9]
	v_lshl_add_u64 v[224:225], v[224:225], 0, s[8:9]
	s_waitcnt vmcnt(6)
	s_waitcnt lgkmcnt(0)
	s_setprio 1
	s_barrier
	v_mfma_f32_16x16x32_bf16 v[62:65], v[154:157], v[188:191], v[62:65]
	v_mfma_f32_16x16x32_bf16 v[58:61], v[164:167], v[188:191], v[58:61]
	v_mfma_f32_16x16x32_bf16 v[54:57], v[154:157], v[196:199], v[54:57]
	v_mfma_f32_16x16x32_bf16 v[46:49], v[164:167], v[196:199], v[46:49]
	v_mfma_f32_16x16x32_bf16 v[38:41], v[154:157], v[204:207], v[38:41]
	v_mfma_f32_16x16x32_bf16 v[30:33], v[164:167], v[204:207], v[30:33]
	v_mfma_f32_16x16x32_bf16 v[22:25], v[154:157], v[212:215], v[22:25]
	v_mfma_f32_16x16x32_bf16 v[14:17], v[164:167], v[212:215], v[14:17]
	v_mfma_f32_16x16x32_bf16 v[62:65], v[158:161], v[192:195], v[62:65]
	v_mfma_f32_16x16x32_bf16 v[58:61], v[168:171], v[192:195], v[58:61]
	v_mfma_f32_16x16x32_bf16 v[54:57], v[158:161], v[200:203], v[54:57]
	v_mfma_f32_16x16x32_bf16 v[46:49], v[168:171], v[200:203], v[46:49]
	v_mfma_f32_16x16x32_bf16 v[38:41], v[158:161], v[208:211], v[38:41]
	v_mfma_f32_16x16x32_bf16 v[30:33], v[168:171], v[208:211], v[30:33]
	v_mfma_f32_16x16x32_bf16 v[22:25], v[158:161], v[216:219], v[22:25]
	v_mfma_f32_16x16x32_bf16 v[14:17], v[168:171], v[216:219], v[14:17]
	v_mfma_f32_16x16x32_bf16 v[50:53], v[172:175], v[188:191], v[50:53]
	v_mfma_f32_16x16x32_bf16 v[42:45], v[180:183], v[188:191], v[42:45]
	v_mfma_f32_16x16x32_bf16 v[34:37], v[172:175], v[196:199], v[34:37]
	v_mfma_f32_16x16x32_bf16 v[26:29], v[180:183], v[196:199], v[26:29]
	v_mfma_f32_16x16x32_bf16 v[18:21], v[172:175], v[204:207], v[18:21]
	v_mfma_f32_16x16x32_bf16 v[10:13], v[180:183], v[204:207], v[10:13]
	v_mfma_f32_16x16x32_bf16 v[6:9], v[172:175], v[212:215], v[6:9]
	v_mfma_f32_16x16x32_bf16 v[2:5], v[180:183], v[212:215], v[2:5]
	v_mfma_f32_16x16x32_bf16 v[50:53], v[176:179], v[192:195], v[50:53]
	v_mfma_f32_16x16x32_bf16 v[42:45], v[184:187], v[192:195], v[42:45]
	v_mfma_f32_16x16x32_bf16 v[34:37], v[176:179], v[200:203], v[34:37]
	v_mfma_f32_16x16x32_bf16 v[26:29], v[184:187], v[200:203], v[26:29]
	v_mfma_f32_16x16x32_bf16 v[18:21], v[176:179], v[208:211], v[18:21]
	v_mfma_f32_16x16x32_bf16 v[10:13], v[184:187], v[208:211], v[10:13]
	v_mfma_f32_16x16x32_bf16 v[6:9], v[176:179], v[216:219], v[6:9]
	v_mfma_f32_16x16x32_bf16 v[2:5], v[184:187], v[216:219], v[2:5]
	s_setprio 0
	s_barrier
	s_add_i32 s53, s53, 2
	s_mov_b32 s32, 1
	s_add_u32 s22, s22, 0x100
	s_addc_u32 s23, s23, 0
	s_add_u32 s51, s51, 0x100
	s_addc_u32 s52, s52, 0
	s_cmpk_gt_u32 s53, 0xa9
	s_cbranch_scc0 .LBB0_1853
	s_and_b64 vcc, exec, s[10:11]
	s_cbranch_vccz .LBB0_1856
	s_barrier

.Lrebal_skip_1983:
	s_add_i32 m0, s29, 0xc000
	s_nop 0
	global_load_lds_dwordx4 v[160:161], off
	v_lshl_add_u64 v[160:161], s[30:31], 0, v[140:141]
	s_add_i32 m0, s29, 0xe000
	s_nop 0
	global_load_lds_dwordx4 v[160:161], off
	s_waitcnt vmcnt(8)
	s_waitcnt lgkmcnt(0)
	s_setprio 1
	s_barrier
	v_mfma_f32_16x16x32_bf16 v[126:129], v[146:149], v[188:191], v[126:129]
	v_mfma_f32_16x16x32_bf16 v[122:125], v[164:167], v[188:191], v[122:125]
	v_mfma_f32_16x16x32_bf16 v[110:113], v[146:149], v[196:199], v[110:113]
	v_mfma_f32_16x16x32_bf16 v[106:109], v[164:167], v[196:199], v[106:109]
	v_mfma_f32_16x16x32_bf16 v[94:97], v[146:149], v[204:207], v[94:97]
	v_mfma_f32_16x16x32_bf16 v[90:93], v[164:167], v[204:207], v[90:93]
	v_mfma_f32_16x16x32_bf16 v[78:81], v[146:149], v[212:215], v[78:81]
	v_mfma_f32_16x16x32_bf16 v[74:77], v[164:167], v[212:215], v[74:77]
	v_mfma_f32_16x16x32_bf16 v[126:129], v[150:153], v[192:195], v[126:129]
	v_mfma_f32_16x16x32_bf16 v[122:125], v[168:171], v[192:195], v[122:125]
	v_mfma_f32_16x16x32_bf16 v[110:113], v[150:153], v[200:203], v[110:113]
	v_mfma_f32_16x16x32_bf16 v[106:109], v[168:171], v[200:203], v[106:109]
	v_mfma_f32_16x16x32_bf16 v[94:97], v[150:153], v[208:211], v[94:97]
	v_mfma_f32_16x16x32_bf16 v[90:93], v[168:171], v[208:211], v[90:93]
	v_mfma_f32_16x16x32_bf16 v[78:81], v[150:153], v[216:219], v[78:81]
	v_mfma_f32_16x16x32_bf16 v[74:77], v[168:171], v[216:219], v[74:77]
	v_mfma_f32_16x16x32_bf16 v[118:121], v[172:175], v[188:191], v[118:121]
	v_mfma_f32_16x16x32_bf16 v[114:117], v[180:183], v[188:191], v[114:117]
	v_mfma_f32_16x16x32_bf16 v[102:105], v[172:175], v[196:199], v[102:105]
	v_mfma_f32_16x16x32_bf16 v[98:101], v[180:183], v[196:199], v[98:101]
	v_mfma_f32_16x16x32_bf16 v[86:89], v[172:175], v[204:207], v[86:89]
	v_mfma_f32_16x16x32_bf16 v[82:85], v[180:183], v[204:207], v[82:85]
	v_mfma_f32_16x16x32_bf16 v[70:73], v[172:175], v[212:215], v[70:73]
	v_mfma_f32_16x16x32_bf16 v[66:69], v[180:183], v[212:215], v[66:69]
	v_mfma_f32_16x16x32_bf16 v[118:121], v[176:179], v[192:195], v[118:121]
	v_mfma_f32_16x16x32_bf16 v[114:117], v[184:187], v[192:195], v[114:117]
	v_mfma_f32_16x16x32_bf16 v[102:105], v[176:179], v[200:203], v[102:105]
	v_mfma_f32_16x16x32_bf16 v[98:101], v[184:187], v[200:203], v[98:101]
	v_mfma_f32_16x16x32_bf16 v[86:89], v[176:179], v[208:211], v[86:89]
	v_mfma_f32_16x16x32_bf16 v[82:85], v[184:187], v[208:211], v[82:85]
	v_mfma_f32_16x16x32_bf16 v[70:73], v[176:179], v[216:219], v[70:73]
	v_mfma_f32_16x16x32_bf16 v[66:69], v[184:187], v[216:219], v[66:69]
	s_setprio 0
	s_barrier
	s_add_i32 s56, s48, s40
	v_lshl_add_u64 v[160:161], s[34:35], 0, v[132:133]
	s_mov_b32 m0, s56
	ds_read_b128 v[188:191], v158 offset:16384
	ds_read_b128 v[192:195], v158 offset:17408
	ds_read_b128 v[196:199], v158 offset:18432
	ds_read_b128 v[200:203], v158 offset:19456
	ds_read_b128 v[204:207], v158 offset:20480
	ds_read_b128 v[208:211], v158 offset:21504
	ds_read_b128 v[212:215], v158 offset:22528
	ds_read_b128 v[216:219], v158 offset:23552
	global_load_lds_dwordx4 v[160:161], off
	s_add_i32 m0, s56, 0x2000
	s_add_u32 s56, s34, 0x100000
	v_lshl_add_u64 v[220:221], s[34:35], 0, v[136:137]
	s_addc_u32 s57, s35, 0
	s_add_i32 s58, s49, s40
	global_load_lds_dwordx4 v[220:221], off
	v_lshl_add_u64 v[222:223], s[56:57], 0, v[132:133]
	s_mov_b32 m0, s58
	v_lshl_add_u64 v[224:225], s[36:37], 0, v[134:135]
	global_load_lds_dwordx4 v[222:223], off
	v_lshl_add_u64 v[222:223], s[56:57], 0, v[136:137]
	s_add_i32 m0, s58, 0x2000
	s_nop 0
	global_load_lds_dwordx4 v[222:223], off
	v_lshl_add_u64 v[222:223], s[36:37], 0, v[130:131]
	s_waitcnt vmcnt(6)
	s_waitcnt lgkmcnt(0)
	s_setprio 1
	s_barrier
	v_mfma_f32_16x16x32_bf16 v[62:65], v[146:149], v[188:191], v[62:65]
	v_mfma_f32_16x16x32_bf16 v[58:61], v[164:167], v[188:191], v[58:61]
	v_mfma_f32_16x16x32_bf16 v[46:49], v[146:149], v[196:199], v[46:49]
	v_mfma_f32_16x16x32_bf16 v[42:45], v[164:167], v[196:199], v[42:45]
	v_mfma_f32_16x16x32_bf16 v[30:33], v[146:149], v[204:207], v[30:33]
	v_mfma_f32_16x16x32_bf16 v[26:29], v[164:167], v[204:207], v[26:29]
	v_mfma_f32_16x16x32_bf16 v[14:17], v[146:149], v[212:215], v[14:17]
	v_mfma_f32_16x16x32_bf16 v[10:13], v[164:167], v[212:215], v[10:13]
	v_mfma_f32_16x16x32_bf16 v[62:65], v[150:153], v[192:195], v[62:65]
	v_mfma_f32_16x16x32_bf16 v[58:61], v[168:171], v[192:195], v[58:61]
	v_mfma_f32_16x16x32_bf16 v[46:49], v[150:153], v[200:203], v[46:49]
	v_mfma_f32_16x16x32_bf16 v[42:45], v[168:171], v[200:203], v[42:45]
	v_mfma_f32_16x16x32_bf16 v[30:33], v[150:153], v[208:211], v[30:33]
	v_mfma_f32_16x16x32_bf16 v[26:29], v[168:171], v[208:211], v[26:29]
	v_mfma_f32_16x16x32_bf16 v[14:17], v[150:153], v[216:219], v[14:17]
	v_mfma_f32_16x16x32_bf16 v[10:13], v[168:171], v[216:219], v[10:13]
	v_mfma_f32_16x16x32_bf16 v[54:57], v[172:175], v[188:191], v[54:57]
	v_mfma_f32_16x16x32_bf16 v[50:53], v[180:183], v[188:191], v[50:53]
	v_mfma_f32_16x16x32_bf16 v[38:41], v[172:175], v[196:199], v[38:41]
	v_mfma_f32_16x16x32_bf16 v[34:37], v[180:183], v[196:199], v[34:37]
	v_mfma_f32_16x16x32_bf16 v[22:25], v[172:175], v[204:207], v[22:25]
	v_mfma_f32_16x16x32_bf16 v[18:21], v[180:183], v[204:207], v[18:21]
	v_mfma_f32_16x16x32_bf16 v[6:9], v[172:175], v[212:215], v[6:9]
	v_mfma_f32_16x16x32_bf16 v[2:5], v[180:183], v[212:215], v[2:5]
	v_mfma_f32_16x16x32_bf16 v[54:57], v[176:179], v[192:195], v[54:57]
	v_mfma_f32_16x16x32_bf16 v[50:53], v[184:187], v[192:195], v[50:53]
	v_mfma_f32_16x16x32_bf16 v[38:41], v[176:179], v[200:203], v[38:41]
	v_mfma_f32_16x16x32_bf16 v[34:37], v[184:187], v[200:203], v[34:37]
	v_mfma_f32_16x16x32_bf16 v[22:25], v[176:179], v[208:211], v[22:25]
	v_mfma_f32_16x16x32_bf16 v[18:21], v[184:187], v[208:211], v[18:21]
	v_mfma_f32_16x16x32_bf16 v[6:9], v[176:179], v[216:219], v[6:9]
	v_mfma_f32_16x16x32_bf16 v[2:5], v[184:187], v[216:219], v[2:5]
	s_setprio 0
	s_barrier
	s_add_i32 s56, 0, 0x18000
	v_add_u32_e32 v159, s56, v154
	s_add_i32 s57, 0, 0x1c000
	ds_read_b128 v[146:149], v159
	ds_read_b128 v[150:153], v159 offset:1024
	ds_read_b128 v[164:167], v159 offset:2048
	ds_read_b128 v[168:171], v159 offset:3072
	v_add_u32_e32 v159, s57, v154
	ds_read_b128 v[172:175], v159
	ds_read_b128 v[176:179], v159 offset:1024
	ds_read_b128 v[180:183], v159 offset:2048
	ds_read_b128 v[184:187], v159 offset:3072
	s_add_u32 s36, s36, 0x100000
	s_addc_u32 s37, s37, 0
	s_mov_b32 m0, s42
	v_lshl_add_u64 v[226:227], s[36:37], 0, v[130:131]
	ds_read_b128 v[188:191], v158 offset:32768
	ds_read_b128 v[192:195], v158 offset:33792
	ds_read_b128 v[196:199], v158 offset:34816
	ds_read_b128 v[200:203], v158 offset:35840
	ds_read_b128 v[204:207], v158 offset:36864
	ds_read_b128 v[208:211], v158 offset:37888
	ds_read_b128 v[212:215], v158 offset:38912
	ds_read_b128 v[216:219], v158 offset:39936
	s_mov_b32 m0, s29
	s_nop 0
	global_load_lds_dwordx4 v[222:223], off
	s_mov_b32 m0, s41
	s_nop 0
	global_load_lds_dwordx4 v[224:225], off
	s_mov_b32 m0, s42
	s_nop 0
	global_load_lds_dwordx4 v[226:227], off
	v_lshl_add_u64 v[226:227], s[36:37], 0, v[134:135]
	s_mov_b32 m0, s43
	s_nop 0
	global_load_lds_dwordx4 v[226:227], off
	s_waitcnt vmcnt(8)
	s_waitcnt lgkmcnt(0)
	s_setprio 1
	s_barrier
	v_mfma_f32_16x16x32_bf16 v[126:129], v[146:149], v[188:191], v[126:129]
	v_mfma_f32_16x16x32_bf16 v[122:125], v[164:167], v[188:191], v[122:125]
	v_mfma_f32_16x16x32_bf16 v[110:113], v[146:149], v[196:199], v[110:113]
	v_mfma_f32_16x16x32_bf16 v[106:109], v[164:167], v[196:199], v[106:109]
	v_mfma_f32_16x16x32_bf16 v[94:97], v[146:149], v[204:207], v[94:97]
	v_mfma_f32_16x16x32_bf16 v[90:93], v[164:167], v[204:207], v[90:93]
	v_mfma_f32_16x16x32_bf16 v[78:81], v[146:149], v[212:215], v[78:81]
	v_mfma_f32_16x16x32_bf16 v[74:77], v[164:167], v[212:215], v[74:77]
	v_mfma_f32_16x16x32_bf16 v[126:129], v[150:153], v[192:195], v[126:129]
	v_mfma_f32_16x16x32_bf16 v[122:125], v[168:171], v[192:195], v[122:125]
	v_mfma_f32_16x16x32_bf16 v[110:113], v[150:153], v[200:203], v[110:113]
	v_mfma_f32_16x16x32_bf16 v[106:109], v[168:171], v[200:203], v[106:109]
	v_mfma_f32_16x16x32_bf16 v[94:97], v[150:153], v[208:211], v[94:97]
	v_mfma_f32_16x16x32_bf16 v[90:93], v[168:171], v[208:211], v[90:93]
	v_mfma_f32_16x16x32_bf16 v[78:81], v[150:153], v[216:219], v[78:81]
	v_mfma_f32_16x16x32_bf16 v[74:77], v[168:171], v[216:219], v[74:77]
	v_mfma_f32_16x16x32_bf16 v[118:121], v[172:175], v[188:191], v[118:121]
	v_mfma_f32_16x16x32_bf16 v[114:117], v[180:183], v[188:191], v[114:117]
	v_mfma_f32_16x16x32_bf16 v[102:105], v[172:175], v[196:199], v[102:105]
	v_mfma_f32_16x16x32_bf16 v[98:101], v[180:183], v[196:199], v[98:101]
	v_mfma_f32_16x16x32_bf16 v[86:89], v[172:175], v[204:207], v[86:89]
	v_mfma_f32_16x16x32_bf16 v[82:85], v[180:183], v[204:207], v[82:85]
	v_mfma_f32_16x16x32_bf16 v[70:73], v[172:175], v[212:215], v[70:73]
	v_mfma_f32_16x16x32_bf16 v[66:69], v[180:183], v[212:215], v[66:69]
	v_mfma_f32_16x16x32_bf16 v[118:121], v[176:179], v[192:195], v[118:121]
	v_mfma_f32_16x16x32_bf16 v[114:117], v[184:187], v[192:195], v[114:117]
	v_mfma_f32_16x16x32_bf16 v[102:105], v[176:179], v[200:203], v[102:105]
	v_mfma_f32_16x16x32_bf16 v[98:101], v[184:187], v[200:203], v[98:101]
	v_mfma_f32_16x16x32_bf16 v[86:89], v[176:179], v[208:211], v[86:89]
	v_mfma_f32_16x16x32_bf16 v[82:85], v[184:187], v[208:211], v[82:85]
	v_mfma_f32_16x16x32_bf16 v[70:73], v[176:179], v[216:219], v[70:73]
	v_mfma_f32_16x16x32_bf16 v[66:69], v[184:187], v[216:219], v[66:69]
	s_setprio 0
	s_barrier
	s_add_i32 s36, s56, s40
	v_lshl_add_u64 v[160:161], v[160:161], 0, s[10:11]
	s_mov_b32 m0, s36
	ds_read_b128 v[188:191], v158 offset:49152
	ds_read_b128 v[192:195], v158 offset:50176
	ds_read_b128 v[196:199], v158 offset:51200
	ds_read_b128 v[200:203], v158 offset:52224
	ds_read_b128 v[204:207], v158 offset:53248
	ds_read_b128 v[208:211], v158 offset:54272
	ds_read_b128 v[212:215], v158 offset:55296
	ds_read_b128 v[216:219], v158 offset:56320
	global_load_lds_dwordx4 v[160:161], off
	s_add_i32 m0, s36, 0x2000
	s_add_u32 s34, s34, 0x100080
	v_lshl_add_u64 v[160:161], v[220:221], 0, s[10:11]
	s_addc_u32 s35, s35, 0
	s_add_i32 s36, s57, s40
	global_load_lds_dwordx4 v[160:161], off
	v_lshl_add_u64 v[160:161], s[34:35], 0, v[132:133]
	s_mov_b32 m0, s36
	s_nop 0
	global_load_lds_dwordx4 v[160:161], off
	v_lshl_add_u64 v[160:161], s[34:35], 0, v[136:137]
	s_add_i32 m0, s36, 0x2000
	s_nop 0
	global_load_lds_dwordx4 v[160:161], off
	v_lshl_add_u64 v[222:223], v[222:223], 0, s[10:11]
	v_lshl_add_u64 v[224:225], v[224:225], 0, s[10:11]
	s_waitcnt vmcnt(6)
	s_waitcnt lgkmcnt(0)
	s_setprio 1
	s_barrier
	v_mfma_f32_16x16x32_bf16 v[62:65], v[146:149], v[188:191], v[62:65]
	v_mfma_f32_16x16x32_bf16 v[58:61], v[164:167], v[188:191], v[58:61]
	v_mfma_f32_16x16x32_bf16 v[46:49], v[146:149], v[196:199], v[46:49]
	v_mfma_f32_16x16x32_bf16 v[42:45], v[164:167], v[196:199], v[42:45]
	v_mfma_f32_16x16x32_bf16 v[30:33], v[146:149], v[204:207], v[30:33]
	v_mfma_f32_16x16x32_bf16 v[26:29], v[164:167], v[204:207], v[26:29]
	v_mfma_f32_16x16x32_bf16 v[14:17], v[146:149], v[212:215], v[14:17]
	v_mfma_f32_16x16x32_bf16 v[10:13], v[164:167], v[212:215], v[10:13]
	v_mfma_f32_16x16x32_bf16 v[62:65], v[150:153], v[192:195], v[62:65]
	v_mfma_f32_16x16x32_bf16 v[58:61], v[168:171], v[192:195], v[58:61]
	v_mfma_f32_16x16x32_bf16 v[46:49], v[150:153], v[200:203], v[46:49]
	v_mfma_f32_16x16x32_bf16 v[42:45], v[168:171], v[200:203], v[42:45]
	v_mfma_f32_16x16x32_bf16 v[30:33], v[150:153], v[208:211], v[30:33]
	v_mfma_f32_16x16x32_bf16 v[26:29], v[168:171], v[208:211], v[26:29]
	v_mfma_f32_16x16x32_bf16 v[14:17], v[150:153], v[216:219], v[14:17]
	v_mfma_f32_16x16x32_bf16 v[10:13], v[168:171], v[216:219], v[10:13]
	v_mfma_f32_16x16x32_bf16 v[54:57], v[172:175], v[188:191], v[54:57]
	v_mfma_f32_16x16x32_bf16 v[50:53], v[180:183], v[188:191], v[50:53]
	v_mfma_f32_16x16x32_bf16 v[38:41], v[172:175], v[196:199], v[38:41]
	v_mfma_f32_16x16x32_bf16 v[34:37], v[180:183], v[196:199], v[34:37]
	v_mfma_f32_16x16x32_bf16 v[22:25], v[172:175], v[204:207], v[22:25]
	v_mfma_f32_16x16x32_bf16 v[18:21], v[180:183], v[204:207], v[18:21]
	v_mfma_f32_16x16x32_bf16 v[6:9], v[172:175], v[212:215], v[6:9]
	v_mfma_f32_16x16x32_bf16 v[2:5], v[180:183], v[212:215], v[2:5]
	v_mfma_f32_16x16x32_bf16 v[54:57], v[176:179], v[192:195], v[54:57]
	v_mfma_f32_16x16x32_bf16 v[50:53], v[184:187], v[192:195], v[50:53]
	v_mfma_f32_16x16x32_bf16 v[38:41], v[176:179], v[200:203], v[38:41]
	v_mfma_f32_16x16x32_bf16 v[34:37], v[184:187], v[200:203], v[34:37]
	v_mfma_f32_16x16x32_bf16 v[22:25], v[176:179], v[208:211], v[22:25]
	v_mfma_f32_16x16x32_bf16 v[18:21], v[184:187], v[208:211], v[18:21]
	v_mfma_f32_16x16x32_bf16 v[6:9], v[176:179], v[216:219], v[6:9]
	v_mfma_f32_16x16x32_bf16 v[2:5], v[184:187], v[216:219], v[2:5]
	s_setprio 0
	s_barrier
	s_add_i32 s55, s55, 2
	s_mov_b32 s32, 1
	s_add_u32 s30, s30, 0x100
	s_addc_u32 s31, s31, 0
	s_add_u32 s53, s53, 0x100
	s_addc_u32 s54, s54, 0
	s_cmp_gt_u32 s55, 61
	s_cbranch_scc0 .LBB0_1983
	s_and_b64 vcc, exec, s[12:13]
	s_cbranch_vccz .LBB0_1986
	s_barrier
